# phase-11 sample-row partial sums batched; prep0 gain vectors hoisted; diff-attention epilogue gain loads and phase_post GLA-operand loads batched; GEMM first K iteration peeled with SrcC=0 (no per-til
# speedup vs baseline: 1.1864x; 1.0111x over previous
; __device__ __forceinline__ void load_row(const Params& p, int r, int mode, int lane, f32x4 (&v)[8]) {
;     float* X = p.out;
;     if (r < TP) {
; #pragma unroll
;         for (int j = 0; j < 8; ++j) v[j] = ((const f32x4*)(X + (size_t)r * DM))[j * 64 + lane];
;     } else {
;         const float* base = mode == 0 ? p.in[1] + (size_t)(r - TP) * DM : X + (size_t)r * DM;
;         const float alpha = mode == 1 ? 1.0f : 0.5f;
;         const float* P = (const float*)(p.ws + WS_PART) + (size_t)(r - TP) * DM;
; #pragma unroll
;         for (int j = 0; j < 8; ++j) {
;             f32x4 a = (f32x4){0.f, 0.f, 0.f, 0.f};
; #pragma unroll
;             for (int q = 0; q < 8; ++q) a += ((const f32x4*)(P + (size_t)q * 512 * DM))[j * 64 + lane];
;             v[j] = ((const f32x4*)base)[j * 64 + lane] + alpha * a;
.LBB0_19:
	v_cmp_lt_i32_e32 vcc, s81, v34
	v_lshlrev_b32_e32 v0, 4, v36
	s_and_saveexec_b64 s[16:17], vcc
	s_xor_b64 s[16:17], exec, s[16:17]
	s_cbranch_execz .LBB0_21
	s_load_dwordx2 s[52:53], s[68:69], 0xf0
	v_mov_b32_e32 v35, v1
	v_lshlrev_b64 v[60:61], 13, v[34:35]
	v_add_u32_e32 v2, 0xffffc000, v34
	v_mov_b32_e32 v3, v1
	v_lshlrev_b64 v[2:3], 13, v[2:3]
	v_mov_b32_e32 v53, v1
	v_mov_b32_e32 v55, v1
	v_mov_b32_e32 v57, v1
	v_mov_b32_e32 v59, v1
	s_waitcnt vmcnt(0) lgkmcnt(0)
	v_lshl_add_u64 v[162:163], s[10:11], 0, v[2:3]
	v_lshl_add_u64 v[162:163], v[162:163], 0, v[0:1]
	v_lshl_add_u64 v[160:161], s[52:53], 0, v[60:61]
	v_lshl_add_u64 v[160:161], v[160:161], 0, v[0:1]
	s_mov_b32 s54, 0x400000
	s_mov_b32 s55, 0
	s_mov_b32 s56, 0x1000
	s_mov_b32 s57, 0
	v_mov_b64_e32 v[158:159], v[162:163]
	v_mov_b64_e32 v[164:165], v[160:161]
	global_load_dwordx4 v[86:89], v[158:159], off
	global_load_dwordx4 v[90:93], v[158:159], off offset:1024
	v_lshl_add_u64 v[158:159], v[158:159], 0, s[54:55]
	global_load_dwordx4 v[94:97], v[158:159], off
	global_load_dwordx4 v[98:101], v[158:159], off offset:1024
	v_lshl_add_u64 v[158:159], v[158:159], 0, s[54:55]
	global_load_dwordx4 v[102:105], v[158:159], off
	global_load_dwordx4 v[106:109], v[158:159], off offset:1024
	v_lshl_add_u64 v[158:159], v[158:159], 0, s[54:55]
	global_load_dwordx4 v[110:113], v[158:159], off
	global_load_dwordx4 v[114:117], v[158:159], off offset:1024
	v_lshl_add_u64 v[158:159], v[158:159], 0, s[54:55]
	global_load_dwordx4 v[118:121], v[158:159], off
	global_load_dwordx4 v[122:125], v[158:159], off offset:1024
	v_lshl_add_u64 v[158:159], v[158:159], 0, s[54:55]
	global_load_dwordx4 v[126:129], v[158:159], off
	global_load_dwordx4 v[130:133], v[158:159], off offset:1024
	v_lshl_add_u64 v[158:159], v[158:159], 0, s[54:55]
	global_load_dwordx4 v[134:137], v[158:159], off
	global_load_dwordx4 v[138:141], v[158:159], off offset:1024
	v_lshl_add_u64 v[158:159], v[158:159], 0, s[54:55]
	global_load_dwordx4 v[142:145], v[158:159], off
	global_load_dwordx4 v[146:149], v[158:159], off offset:1024
	global_load_dwordx4 v[150:153], v[164:165], off
	global_load_dwordx4 v[154:157], v[164:165], off offset:1024
	s_waitcnt vmcnt(0)
	v_pk_add_f32 v[88:89], v[88:89], 0 op_sel_hi:[1,0]
	v_pk_add_f32 v[86:87], v[86:87], 0 op_sel_hi:[1,0]
	v_pk_add_f32 v[88:89], v[88:89], v[96:97]
	v_pk_add_f32 v[86:87], v[86:87], v[94:95]
	v_pk_add_f32 v[88:89], v[88:89], v[104:105]
	v_pk_add_f32 v[86:87], v[86:87], v[102:103]
	v_pk_add_f32 v[88:89], v[88:89], v[112:113]
	v_pk_add_f32 v[86:87], v[86:87], v[110:111]
	v_pk_add_f32 v[88:89], v[88:89], v[120:121]
	v_pk_add_f32 v[86:87], v[86:87], v[118:119]
	v_pk_add_f32 v[88:89], v[88:89], v[128:129]
	v_pk_add_f32 v[86:87], v[86:87], v[126:127]
	v_pk_add_f32 v[88:89], v[88:89], v[136:137]
	v_pk_add_f32 v[86:87], v[86:87], v[134:135]
	v_pk_add_f32 v[88:89], v[88:89], v[144:145]
	v_pk_add_f32 v[86:87], v[86:87], v[142:143]
	v_pk_fma_f32 v[8:9], v[88:89], 0.5, v[152:153] op_sel_hi:[1,0,1]
	v_pk_fma_f32 v[6:7], v[86:87], 0.5, v[150:151] op_sel_hi:[1,0,1]
	v_pk_add_f32 v[92:93], v[92:93], 0 op_sel_hi:[1,0]
	v_pk_add_f32 v[90:91], v[90:91], 0 op_sel_hi:[1,0]
	v_pk_add_f32 v[92:93], v[92:93], v[100:101]
	v_pk_add_f32 v[90:91], v[90:91], v[98:99]
	v_pk_add_f32 v[92:93], v[92:93], v[108:109]
	v_pk_add_f32 v[90:91], v[90:91], v[106:107]
	v_pk_add_f32 v[92:93], v[92:93], v[116:117]
	v_pk_add_f32 v[90:91], v[90:91], v[114:115]
	v_pk_add_f32 v[92:93], v[92:93], v[124:125]
	v_pk_add_f32 v[90:91], v[90:91], v[122:123]
	v_pk_add_f32 v[92:93], v[92:93], v[132:133]
	v_pk_add_f32 v[90:91], v[90:91], v[130:131]
	v_pk_add_f32 v[92:93], v[92:93], v[140:141]
	v_pk_add_f32 v[90:91], v[90:91], v[138:139]
	v_pk_add_f32 v[92:93], v[92:93], v[148:149]
	v_pk_add_f32 v[90:91], v[90:91], v[146:147]
	v_pk_fma_f32 v[4:5], v[92:93], 0.5, v[156:157] op_sel_hi:[1,0,1]
	v_pk_fma_f32 v[2:3], v[90:91], 0.5, v[154:155] op_sel_hi:[1,0,1]
	v_mov_b64_e32 v[158:159], v[162:163]
	v_mov_b64_e32 v[164:165], v[160:161]
	global_load_dwordx4 v[86:89], v[158:159], off offset:2048
	global_load_dwordx4 v[90:93], v[158:159], off offset:3072
	v_lshl_add_u64 v[158:159], v[158:159], 0, s[54:55]
	global_load_dwordx4 v[94:97], v[158:159], off offset:2048
	global_load_dwordx4 v[98:101], v[158:159], off offset:3072
	v_lshl_add_u64 v[158:159], v[158:159], 0, s[54:55]
	global_load_dwordx4 v[102:105], v[158:159], off offset:2048
	global_load_dwordx4 v[106:109], v[158:159], off offset:3072
	v_lshl_add_u64 v[158:159], v[158:159], 0, s[54:55]
	global_load_dwordx4 v[110:113], v[158:159], off offset:2048
	global_load_dwordx4 v[114:117], v[158:159], off offset:3072
	v_lshl_add_u64 v[158:159], v[158:159], 0, s[54:55]
	global_load_dwordx4 v[118:121], v[158:159], off offset:2048
	global_load_dwordx4 v[122:125], v[158:159], off offset:3072
	v_lshl_add_u64 v[158:159], v[158:159], 0, s[54:55]
	global_load_dwordx4 v[126:129], v[158:159], off offset:2048
	global_load_dwordx4 v[130:133], v[158:159], off offset:3072
	v_lshl_add_u64 v[158:159], v[158:159], 0, s[54:55]
	global_load_dwordx4 v[134:137], v[158:159], off offset:2048
	global_load_dwordx4 v[138:141], v[158:159], off offset:3072
	v_lshl_add_u64 v[158:159], v[158:159], 0, s[54:55]
	global_load_dwordx4 v[142:145], v[158:159], off offset:2048
	global_load_dwordx4 v[146:149], v[158:159], off offset:3072
	global_load_dwordx4 v[150:153], v[164:165], off offset:2048
	global_load_dwordx4 v[154:157], v[164:165], off offset:3072
	s_waitcnt vmcnt(0)
; __device__ __forceinline__ void load_row(const Params& p, int r, int mode, int lane, f32x4 (&v)[8]) {
;     ...
;         for (int j = 0; j < 8; ++j) {
;             f32x4 a = (f32x4){0.f, 0.f, 0.f, 0.f};
; #pragma unroll
;             for (int q = 0; q < 8; ++q) a += ((const f32x4*)(P + (size_t)q * 512 * DM))[j * 64 + lane];
;             v[j] = ((const f32x4*)base)[j * 64 + lane] + alpha * a;
	v_pk_add_f32 v[88:89], v[88:89], 0 op_sel_hi:[1,0]
	v_pk_add_f32 v[86:87], v[86:87], 0 op_sel_hi:[1,0]
	v_pk_add_f32 v[88:89], v[88:89], v[96:97]
	v_pk_add_f32 v[86:87], v[86:87], v[94:95]
	v_pk_add_f32 v[88:89], v[88:89], v[104:105]
	v_pk_add_f32 v[86:87], v[86:87], v[102:103]
	v_pk_add_f32 v[88:89], v[88:89], v[112:113]
	v_pk_add_f32 v[86:87], v[86:87], v[110:111]
	v_pk_add_f32 v[88:89], v[88:89], v[120:121]
	v_pk_add_f32 v[86:87], v[86:87], v[118:119]
	v_pk_add_f32 v[88:89], v[88:89], v[128:129]
	v_pk_add_f32 v[86:87], v[86:87], v[126:127]
	v_pk_add_f32 v[88:89], v[88:89], v[136:137]
	v_pk_add_f32 v[86:87], v[86:87], v[134:135]
	v_pk_add_f32 v[88:89], v[88:89], v[144:145]
	v_pk_add_f32 v[86:87], v[86:87], v[142:143]
	v_pk_fma_f32 v[12:13], v[88:89], 0.5, v[152:153] op_sel_hi:[1,0,1]
	v_pk_fma_f32 v[10:11], v[86:87], 0.5, v[150:151] op_sel_hi:[1,0,1]
	v_pk_add_f32 v[92:93], v[92:93], 0 op_sel_hi:[1,0]
	v_pk_add_f32 v[90:91], v[90:91], 0 op_sel_hi:[1,0]
	v_pk_add_f32 v[92:93], v[92:93], v[100:101]
	v_pk_add_f32 v[90:91], v[90:91], v[98:99]
	v_pk_add_f32 v[92:93], v[92:93], v[108:109]
	v_pk_add_f32 v[90:91], v[90:91], v[106:107]
	v_pk_add_f32 v[92:93], v[92:93], v[116:117]
	v_pk_add_f32 v[90:91], v[90:91], v[114:115]
	v_pk_add_f32 v[92:93], v[92:93], v[124:125]
	v_pk_add_f32 v[90:91], v[90:91], v[122:123]
	v_pk_add_f32 v[92:93], v[92:93], v[132:133]
	v_pk_add_f32 v[90:91], v[90:91], v[130:131]
	v_pk_add_f32 v[92:93], v[92:93], v[140:141]
	v_pk_add_f32 v[90:91], v[90:91], v[138:139]
	v_pk_add_f32 v[92:93], v[92:93], v[148:149]
	v_pk_add_f32 v[90:91], v[90:91], v[146:147]
	v_pk_fma_f32 v[16:17], v[92:93], 0.5, v[156:157] op_sel_hi:[1,0,1]
	v_pk_fma_f32 v[14:15], v[90:91], 0.5, v[154:155] op_sel_hi:[1,0,1]
	v_lshl_add_u64 v[158:159], v[162:163], 0, s[56:57]
	v_lshl_add_u64 v[164:165], v[160:161], 0, s[56:57]
	global_load_dwordx4 v[86:89], v[158:159], off
	global_load_dwordx4 v[90:93], v[158:159], off offset:1024
	v_lshl_add_u64 v[158:159], v[158:159], 0, s[54:55]
	global_load_dwordx4 v[94:97], v[158:159], off
	global_load_dwordx4 v[98:101], v[158:159], off offset:1024
	v_lshl_add_u64 v[158:159], v[158:159], 0, s[54:55]
	global_load_dwordx4 v[102:105], v[158:159], off
	global_load_dwordx4 v[106:109], v[158:159], off offset:1024
	v_lshl_add_u64 v[158:159], v[158:159], 0, s[54:55]
	global_load_dwordx4 v[110:113], v[158:159], off
	global_load_dwordx4 v[114:117], v[158:159], off offset:1024
	v_lshl_add_u64 v[158:159], v[158:159], 0, s[54:55]
	global_load_dwordx4 v[118:121], v[158:159], off
	global_load_dwordx4 v[122:125], v[158:159], off offset:1024
	v_lshl_add_u64 v[158:159], v[158:159], 0, s[54:55]
	global_load_dwordx4 v[126:129], v[158:159], off
	global_load_dwordx4 v[130:133], v[158:159], off offset:1024
	v_lshl_add_u64 v[158:159], v[158:159], 0, s[54:55]
	global_load_dwordx4 v[134:137], v[158:159], off
	global_load_dwordx4 v[138:141], v[158:159], off offset:1024
	v_lshl_add_u64 v[158:159], v[158:159], 0, s[54:55]
	global_load_dwordx4 v[142:145], v[158:159], off
	global_load_dwordx4 v[146:149], v[158:159], off offset:1024
	global_load_dwordx4 v[150:153], v[164:165], off
	global_load_dwordx4 v[154:157], v[164:165], off offset:1024
	s_waitcnt vmcnt(0)
; __device__ __forceinline__ void load_row(const Params& p, int r, int mode, int lane, f32x4 (&v)[8]) {
;     ...
;         for (int j = 0; j < 8; ++j) {
;             f32x4 a = (f32x4){0.f, 0.f, 0.f, 0.f};
; #pragma unroll
;             for (int q = 0; q < 8; ++q) a += ((const f32x4*)(P + (size_t)q * 512 * DM))[j * 64 + lane];
;             v[j] = ((const f32x4*)base)[j * 64 + lane] + alpha * a;
	v_pk_add_f32 v[88:89], v[88:89], 0 op_sel_hi:[1,0]
	v_pk_add_f32 v[86:87], v[86:87], 0 op_sel_hi:[1,0]
	v_pk_add_f32 v[88:89], v[88:89], v[96:97]
	v_pk_add_f32 v[86:87], v[86:87], v[94:95]
	v_pk_add_f32 v[88:89], v[88:89], v[104:105]
	v_pk_add_f32 v[86:87], v[86:87], v[102:103]
	v_pk_add_f32 v[88:89], v[88:89], v[112:113]
	v_pk_add_f32 v[86:87], v[86:87], v[110:111]
	v_pk_add_f32 v[88:89], v[88:89], v[120:121]
	v_pk_add_f32 v[86:87], v[86:87], v[118:119]
	v_pk_add_f32 v[88:89], v[88:89], v[128:129]
	v_pk_add_f32 v[86:87], v[86:87], v[126:127]
	v_pk_add_f32 v[88:89], v[88:89], v[136:137]
	v_pk_add_f32 v[86:87], v[86:87], v[134:135]
	v_pk_add_f32 v[88:89], v[88:89], v[144:145]
	v_pk_add_f32 v[86:87], v[86:87], v[142:143]
	v_pk_fma_f32 v[20:21], v[88:89], 0.5, v[152:153] op_sel_hi:[1,0,1]
	v_pk_fma_f32 v[18:19], v[86:87], 0.5, v[150:151] op_sel_hi:[1,0,1]
	v_pk_add_f32 v[92:93], v[92:93], 0 op_sel_hi:[1,0]
	v_pk_add_f32 v[90:91], v[90:91], 0 op_sel_hi:[1,0]
	v_pk_add_f32 v[92:93], v[92:93], v[100:101]
	v_pk_add_f32 v[90:91], v[90:91], v[98:99]
	v_pk_add_f32 v[92:93], v[92:93], v[108:109]
	v_pk_add_f32 v[90:91], v[90:91], v[106:107]
	v_pk_add_f32 v[92:93], v[92:93], v[116:117]
	v_pk_add_f32 v[90:91], v[90:91], v[114:115]
	v_pk_add_f32 v[92:93], v[92:93], v[124:125]
	v_pk_add_f32 v[90:91], v[90:91], v[122:123]
	v_pk_add_f32 v[92:93], v[92:93], v[132:133]
	v_pk_add_f32 v[90:91], v[90:91], v[130:131]
	v_pk_add_f32 v[92:93], v[92:93], v[140:141]
	v_pk_add_f32 v[90:91], v[90:91], v[138:139]
	v_pk_add_f32 v[92:93], v[92:93], v[148:149]
	v_pk_add_f32 v[90:91], v[90:91], v[146:147]
	v_pk_fma_f32 v[24:25], v[92:93], 0.5, v[156:157] op_sel_hi:[1,0,1]
	v_pk_fma_f32 v[22:23], v[90:91], 0.5, v[154:155] op_sel_hi:[1,0,1]
	v_lshl_add_u64 v[158:159], v[162:163], 0, s[56:57]
	v_lshl_add_u64 v[164:165], v[160:161], 0, s[56:57]
	global_load_dwordx4 v[86:89], v[158:159], off offset:2048
	global_load_dwordx4 v[90:93], v[158:159], off offset:3072
	v_lshl_add_u64 v[158:159], v[158:159], 0, s[54:55]
	global_load_dwordx4 v[94:97], v[158:159], off offset:2048
	global_load_dwordx4 v[98:101], v[158:159], off offset:3072
	v_lshl_add_u64 v[158:159], v[158:159], 0, s[54:55]
	global_load_dwordx4 v[102:105], v[158:159], off offset:2048
	global_load_dwordx4 v[106:109], v[158:159], off offset:3072
	v_lshl_add_u64 v[158:159], v[158:159], 0, s[54:55]
	global_load_dwordx4 v[110:113], v[158:159], off offset:2048
	global_load_dwordx4 v[114:117], v[158:159], off offset:3072
	v_lshl_add_u64 v[158:159], v[158:159], 0, s[54:55]
	global_load_dwordx4 v[118:121], v[158:159], off offset:2048
	global_load_dwordx4 v[122:125], v[158:159], off offset:3072
	v_lshl_add_u64 v[158:159], v[158:159], 0, s[54:55]
	global_load_dwordx4 v[126:129], v[158:159], off offset:2048
	global_load_dwordx4 v[130:133], v[158:159], off offset:3072
	v_lshl_add_u64 v[158:159], v[158:159], 0, s[54:55]
	global_load_dwordx4 v[134:137], v[158:159], off offset:2048
	global_load_dwordx4 v[138:141], v[158:159], off offset:3072
	v_lshl_add_u64 v[158:159], v[158:159], 0, s[54:55]
	global_load_dwordx4 v[142:145], v[158:159], off offset:2048
	global_load_dwordx4 v[146:149], v[158:159], off offset:3072
	global_load_dwordx4 v[150:153], v[164:165], off offset:2048
	global_load_dwordx4 v[154:157], v[164:165], off offset:3072
	s_waitcnt vmcnt(0)
	v_pk_add_f32 v[88:89], v[88:89], 0 op_sel_hi:[1,0]
	v_pk_add_f32 v[86:87], v[86:87], 0 op_sel_hi:[1,0]
	v_pk_add_f32 v[88:89], v[88:89], v[96:97]
	v_pk_add_f32 v[86:87], v[86:87], v[94:95]
	v_pk_add_f32 v[88:89], v[88:89], v[104:105]
	v_pk_add_f32 v[86:87], v[86:87], v[102:103]
	v_pk_add_f32 v[88:89], v[88:89], v[112:113]
	v_pk_add_f32 v[86:87], v[86:87], v[110:111]
	v_pk_add_f32 v[88:89], v[88:89], v[120:121]
	v_pk_add_f32 v[86:87], v[86:87], v[118:119]
	v_pk_add_f32 v[88:89], v[88:89], v[128:129]
	v_pk_add_f32 v[86:87], v[86:87], v[126:127]
	v_pk_add_f32 v[88:89], v[88:89], v[136:137]
	v_pk_add_f32 v[86:87], v[86:87], v[134:135]
	v_pk_add_f32 v[88:89], v[88:89], v[144:145]
	v_pk_add_f32 v[86:87], v[86:87], v[142:143]
	v_pk_fma_f32 v[28:29], v[88:89], 0.5, v[152:153] op_sel_hi:[1,0,1]
	v_pk_fma_f32 v[26:27], v[86:87], 0.5, v[150:151] op_sel_hi:[1,0,1]
	v_pk_add_f32 v[92:93], v[92:93], 0 op_sel_hi:[1,0]
	v_pk_add_f32 v[90:91], v[90:91], 0 op_sel_hi:[1,0]
	v_pk_add_f32 v[92:93], v[92:93], v[100:101]
	v_pk_add_f32 v[90:91], v[90:91], v[98:99]
	v_pk_add_f32 v[92:93], v[92:93], v[108:109]
	v_pk_add_f32 v[90:91], v[90:91], v[106:107]
	v_pk_add_f32 v[92:93], v[92:93], v[116:117]
	v_pk_add_f32 v[90:91], v[90:91], v[114:115]
	v_pk_add_f32 v[92:93], v[92:93], v[124:125]
	v_pk_add_f32 v[90:91], v[90:91], v[122:123]
	v_pk_add_f32 v[92:93], v[92:93], v[132:133]
	v_pk_add_f32 v[90:91], v[90:91], v[130:131]
	v_pk_add_f32 v[92:93], v[92:93], v[140:141]
	v_pk_add_f32 v[90:91], v[90:91], v[138:139]
	v_pk_add_f32 v[92:93], v[92:93], v[148:149]
	v_pk_add_f32 v[90:91], v[90:91], v[146:147]
	v_pk_fma_f32 v[32:33], v[92:93], 0.5, v[156:157] op_sel_hi:[1,0,1]
	v_pk_fma_f32 v[30:31], v[90:91], 0.5, v[154:155] op_sel_hi:[1,0,1]

; #define BAR_LDS() do { asm volatile("s_waitcnt lgkmcnt(0)" ::: "memory"); __builtin_amdgcn_s_barrier(); asm volatile("" ::: "memory"); } while (0)
; template <int MODE>
; __device__ __forceinline__ void attn_item(const Params& p, unsigned char* sm, int h, int tok0, int nrows, int kvt0, int ntiles, int nkeys, int qpos0, const int TIDX) {
;     ...
;         const float d1 = wave_sum(L[lane] * L[64 + lane]), d2 = wave_sum(L[128 + lane] * L[192 + lane]);
;         const float lam_init = 0.2f, lam = __expf(d1) - __expf(d2) + lam_init;
;         if (c == 1) {
; #pragma unroll
;             for (int cb = 0; cb < 8; ++cb) *(f32x4*)(XCH + (rg * 16 + r16) * 132 + 16 * cb + 4 * g) = O[cb] * inv;
;         }
;         BAR_LDS();
;         if (c == 0) {
;             float ss = 0.f;
; #pragma unroll
;             for (int cb = 0; cb < 8; ++cb) { const f32x4 x1 = *(const f32x4*)(XCH + (rg * 16 + r16) * 132 + 16 * cb + 4 * g); O[cb] = O[cb] * inv - lam * x1;
;                 ss += O[cb][0] * O[cb][0] + O[cb][1] * O[cb][1] + O[cb][2] * O[cb][2] + O[cb][3] * O[cb][3]; }
;             ss += __shfl_xor(ss, 16); ss += __shfl_xor(ss, 32);
.LBB0_108:
	s_waitcnt lgkmcnt(0)
	s_barrier
	s_andn2_b64 vcc, exec, s[10:11]
	s_cbranch_vccnz .LBB0_112
	v_add_f32_e32 v0, v36, v37
	s_waitcnt lgkmcnt(0)
	v_add_f32_e32 v36, v38, v39
	v_mul_f32_e32 v0, 0x3fb8aa3b, v0
	v_mul_f32_e32 v36, 0x3fb8aa3b, v36
	v_exp_f32_e32 v0, v0
	v_exp_f32_e32 v36, v36
	s_nop 0
	v_sub_f32_e32 v0, v0, v36
	ds_read_b128 v[36:39], v35
	v_add_f32_e32 v0, 0x3e4ccccd, v0
	s_waitcnt lgkmcnt(0)
	v_pk_mul_f32 v[38:39], v[0:1], v[38:39] op_sel_hi:[0,1]
	v_pk_mul_f32 v[40:41], v[0:1], v[36:37] op_sel_hi:[0,1]
	v_pk_fma_f32 v[36:37], v[32:33], v[34:35], v[38:39] op_sel_hi:[1,0,1] neg_lo:[0,0,1] neg_hi:[0,0,1]
	v_pk_fma_f32 v[38:39], v[30:31], v[34:35], v[40:41] op_sel_hi:[1,0,1] neg_lo:[0,0,1] neg_hi:[0,0,1]
	ds_read_b128 v[30:33], v35 offset:64
	v_mul_f32_e32 v42, v39, v39
	v_fmac_f32_e32 v42, v38, v38
	v_fmac_f32_e32 v42, v36, v36
	v_fmac_f32_e32 v42, v37, v37
	s_waitcnt lgkmcnt(0)
	v_pk_mul_f32 v[32:33], v[0:1], v[32:33] op_sel_hi:[0,1]
	v_pk_mul_f32 v[40:41], v[0:1], v[30:31] op_sel_hi:[0,1]
	v_pk_fma_f32 v[30:31], v[24:25], v[34:35], v[32:33] op_sel_hi:[1,0,1] neg_lo:[0,0,1] neg_hi:[0,0,1]
	v_pk_fma_f32 v[32:33], v[22:23], v[34:35], v[40:41] op_sel_hi:[1,0,1] neg_lo:[0,0,1] neg_hi:[0,0,1]
	s_nop 0
	v_mul_f32_e32 v22, v33, v33
	v_fmac_f32_e32 v22, v32, v32
	v_fmac_f32_e32 v22, v30, v30
	v_fmac_f32_e32 v22, v31, v31
	v_add_f32_e32 v42, v42, v22
	ds_read_b128 v[22:25], v35 offset:128
	s_waitcnt lgkmcnt(0)
	v_pk_mul_f32 v[24:25], v[0:1], v[24:25] op_sel_hi:[0,1]
	v_pk_mul_f32 v[40:41], v[0:1], v[22:23] op_sel_hi:[0,1]
	v_pk_fma_f32 v[22:23], v[28:29], v[34:35], v[24:25] op_sel_hi:[1,0,1] neg_lo:[0,0,1] neg_hi:[0,0,1]
	v_pk_fma_f32 v[24:25], v[26:27], v[34:35], v[40:41] op_sel_hi:[1,0,1] neg_lo:[0,0,1] neg_hi:[0,0,1]
	s_nop 0
	v_mul_f32_e32 v26, v25, v25
	v_fmac_f32_e32 v26, v24, v24
	v_fmac_f32_e32 v26, v22, v22
	v_fmac_f32_e32 v26, v23, v23
	v_add_f32_e32 v42, v42, v26
	ds_read_b128 v[26:29], v35 offset:192
	s_waitcnt lgkmcnt(0)
	v_pk_mul_f32 v[28:29], v[0:1], v[28:29] op_sel_hi:[0,1]
	v_pk_mul_f32 v[40:41], v[0:1], v[26:27] op_sel_hi:[0,1]
	v_pk_fma_f32 v[26:27], v[16:17], v[34:35], v[28:29] op_sel_hi:[1,0,1] neg_lo:[0,0,1] neg_hi:[0,0,1]
	v_pk_fma_f32 v[28:29], v[14:15], v[34:35], v[40:41] op_sel_hi:[1,0,1] neg_lo:[0,0,1] neg_hi:[0,0,1]
	s_nop 0
	v_mul_f32_e32 v14, v29, v29
	v_fmac_f32_e32 v14, v28, v28
	v_fmac_f32_e32 v14, v26, v26
	v_fmac_f32_e32 v14, v27, v27
	v_add_f32_e32 v42, v42, v14
	ds_read_b128 v[14:17], v35 offset:256
	s_waitcnt lgkmcnt(0)
	v_pk_mul_f32 v[16:17], v[0:1], v[16:17] op_sel_hi:[0,1]
	v_pk_mul_f32 v[40:41], v[0:1], v[14:15] op_sel_hi:[0,1]
	v_pk_fma_f32 v[14:15], v[20:21], v[34:35], v[16:17] op_sel_hi:[1,0,1] neg_lo:[0,0,1] neg_hi:[0,0,1]
	v_pk_fma_f32 v[16:17], v[18:19], v[34:35], v[40:41] op_sel_hi:[1,0,1] neg_lo:[0,0,1] neg_hi:[0,0,1]
	s_nop 0
	v_mul_f32_e32 v18, v17, v17
	v_fmac_f32_e32 v18, v16, v16
	v_fmac_f32_e32 v18, v14, v14
	v_fmac_f32_e32 v18, v15, v15
	v_add_f32_e32 v42, v42, v18
	ds_read_b128 v[18:21], v35 offset:320
	s_waitcnt lgkmcnt(0)
	v_pk_mul_f32 v[20:21], v[0:1], v[20:21] op_sel_hi:[0,1]
	v_pk_mul_f32 v[40:41], v[0:1], v[18:19] op_sel_hi:[0,1]
	v_pk_fma_f32 v[18:19], v[8:9], v[34:35], v[20:21] op_sel_hi:[1,0,1] neg_lo:[0,0,1] neg_hi:[0,0,1]
	v_pk_fma_f32 v[20:21], v[6:7], v[34:35], v[40:41] op_sel_hi:[1,0,1] neg_lo:[0,0,1] neg_hi:[0,0,1]
	s_nop 0
	v_mul_f32_e32 v6, v21, v21
	v_fmac_f32_e32 v6, v20, v20
	v_fmac_f32_e32 v6, v18, v18
	v_fmac_f32_e32 v6, v19, v19
	v_add_f32_e32 v42, v42, v6
	ds_read_b128 v[6:9], v35 offset:384
	s_waitcnt lgkmcnt(0)
	v_pk_mul_f32 v[8:9], v[0:1], v[8:9] op_sel_hi:[0,1]
	v_pk_mul_f32 v[40:41], v[0:1], v[6:7] op_sel_hi:[0,1]
	v_pk_fma_f32 v[6:7], v[12:13], v[34:35], v[8:9] op_sel_hi:[1,0,1] neg_lo:[0,0,1] neg_hi:[0,0,1]
	v_pk_fma_f32 v[8:9], v[10:11], v[34:35], v[40:41] op_sel_hi:[1,0,1] neg_lo:[0,0,1] neg_hi:[0,0,1]
	s_nop 0
	v_mul_f32_e32 v10, v9, v9
	v_fmac_f32_e32 v10, v8, v8
	v_fmac_f32_e32 v10, v6, v6
	v_fmac_f32_e32 v10, v7, v7
	v_add_f32_e32 v40, v42, v10
	ds_read_b128 v[10:13], v35 offset:448
	s_waitcnt lgkmcnt(0)
	v_pk_mul_f32 v[10:11], v[0:1], v[10:11] op_sel_hi:[0,1]
	v_pk_fma_f32 v[2:3], v[2:3], v[34:35], v[10:11] op_sel_hi:[1,0,1] neg_lo:[0,0,1] neg_hi:[0,0,1]
	v_pk_mul_f32 v[12:13], v[0:1], v[12:13] op_sel_hi:[0,1]
	v_mul_f32_e32 v0, v3, v3
	v_pk_fma_f32 v[4:5], v[4:5], v[34:35], v[12:13] op_sel_hi:[1,0,1] neg_lo:[0,0,1] neg_hi:[0,0,1]
	v_fmac_f32_e32 v0, v2, v2
	v_fmac_f32_e32 v0, v4, v4
	v_fmac_f32_e32 v0, v5, v5
	v_add_f32_e32 v0, v40, v0
	ds_bpermute_b32 v10, v186, v0
	s_waitcnt lgkmcnt(0)
	v_add_f32_e32 v0, v0, v10
	ds_bpermute_b32 v10, v187, v0
	s_and_saveexec_b64 s[10:11], s[6:7]
	s_xor_b64 s[6:7], exec, s[10:11]
	s_cbranch_execz .LBB0_111
; __device__ __forceinline__ unsigned pk2(float lo, float hi) { unsigned r; asm("v_cvt_pk_bf16_f32 %0, %1, %2" : "=v"(r) : "v"(lo), "v"(hi)); return r; }
; template <int MODE>
; __device__ __forceinline__ void attn_item(const Params& p, unsigned char* sm, int h, int tok0, int nrows, int kvt0, int ntiles, int nkeys, int qpos0, const int TIDX) {
;     ...
;             const float rs = rsqrtf(ss * (1.0f / 128) + EPS) * (1.0f - lam_init);
;             if (valid) {
; #pragma unroll
;                 for (int cb = 0; cb < 8; ++cb) { const f32x4 gg = *(const f32x4*)(p.in[20] + 16 * cb + 4 * g);
;                     u32x2 wv; wv.x = pk2(O[cb][0] * rs * gg[0], O[cb][1] * rs * gg[1]); wv.y = pk2(O[cb][2] * rs * gg[2], O[cb][3] * rs * gg[3]);
;                     *(u32x2*)(CAT + (size_t)(tok0 + qrow) * DM + 1024 + h * 128 + 16 * cb + 4 * g) = wv; }
;             }
	s_load_dwordx8 s[20:27], s[68:69], 0x90
	v_lshlrev_b32_e32 v44, 4, v96
	s_waitcnt lgkmcnt(0)
	v_add_f32_e32 v0, v0, v10
	v_fmamk_f32 v0, v0, 0x3c000000, v168
	v_cmp_gt_f32_e32 vcc, s97, v0
	global_load_dwordx4 v[40:43], v44, s[24:25]
	global_load_dwordx4 v[120:123], v44, s[24:25] offset:64
	global_load_dwordx4 v[124:127], v44, s[24:25] offset:128
	global_load_dwordx4 v[128:131], v44, s[24:25] offset:192
	global_load_dwordx4 v[132:135], v44, s[24:25] offset:256
	global_load_dwordx4 v[136:139], v44, s[24:25] offset:320
	global_load_dwordx4 v[140:143], v44, s[24:25] offset:384
	global_load_dwordx4 v[144:147], v44, s[24:25] offset:448
	v_mul_f32_e32 v10, 0x4b800000, v0
	v_cndmask_b32_e32 v0, v0, v10, vcc
	v_rsq_f32_e32 v0, v0
	s_load_dwordx16 s[48:63], s[68:69], 0xc0
	v_readlane_b32 s10, v254, 16
	v_readlane_b32 s11, v254, 17
	v_mul_f32_e32 v10, 0x45800000, v0
	v_cndmask_b32_e32 v0, v0, v10, vcc
	v_add_u32_e32 v10, s96, v75
	v_ashrrev_i32_e32 v11, 31, v10
	v_lshlrev_b64 v[10:11], 12, v[10:11]
	s_waitcnt lgkmcnt(0)
	v_lshl_add_u64 v[10:11], s[62:63], 0, v[10:11]
	s_mov_b32 s13, s11
	s_lshl_b32 s12, s18, 1
	v_mul_f32_e32 v0, 0x3f4ccccd, v0
	v_writelane_b32 v254, s10, 16
	v_lshl_add_u64 v[10:11], v[10:11], 0, s[12:13]
	v_mov_b32_e32 v75, v1
	v_writelane_b32 v254, s11, 17
	v_lshl_add_u64 v[12:13], v[10:11], 0, v[74:75]
	s_mov_b64 s[10:11], 0x6284800
	v_mul_f32_e32 v34, v38, v0
	v_mul_f32_e32 v35, v39, v0
	v_lshl_add_u64 v[10:11], v[12:13], 0, s[10:11]
	s_mov_b32 s10, 0x6284000
	v_add_co_u32_e32 v12, vcc, s10, v12
	v_mul_f32_e32 v8, v8, v0
	s_nop 0
	v_addc_co_u32_e32 v13, vcc, 0, v13, vcc
	v_mul_f32_e32 v9, v9, v0
	v_mul_f32_e32 v6, v6, v0
	v_mul_f32_e32 v7, v7, v0
	v_mul_f32_e32 v2, v2, v0
	v_mul_f32_e32 v3, v3, v0
	s_waitcnt vmcnt(0)
	v_mul_f32_e32 v34, v34, v40
	v_mul_f32_e32 v35, v35, v41
	v_cvt_pk_bf16_f32 v34, v34, v35
	v_mul_f32_e32 v35, v36, v0
	v_mul_f32_e32 v35, v35, v42
	v_mul_f32_e32 v36, v37, v0
	v_mul_f32_e32 v36, v36, v43
	v_cvt_pk_bf16_f32 v35, v35, v36
	global_store_dwordx2 v[12:13], v[34:35], off offset:2048
	v_mov_b64_e32 v[34:35], v[120:121]
	v_mov_b64_e32 v[36:37], v[122:123]
	v_mul_f32_e32 v12, v32, v0
	v_mul_f32_e32 v13, v33, v0
	v_mul_f32_e32 v12, v12, v34
	v_mul_f32_e32 v13, v13, v35
	v_cvt_pk_bf16_f32 v12, v12, v13
	v_mul_f32_e32 v13, v30, v0
	v_mul_f32_e32 v13, v13, v36
	v_mul_f32_e32 v30, v31, v0
	v_mul_f32_e32 v30, v30, v37
	v_cvt_pk_bf16_f32 v13, v13, v30
	global_store_dwordx2 v[10:11], v[12:13], off offset:32
	v_mov_b64_e32 v[30:31], v[124:125]
	v_mov_b64_e32 v[32:33], v[126:127]
	v_mul_f32_e32 v12, v24, v0
	v_mul_f32_e32 v13, v25, v0
	v_mul_f32_e32 v12, v12, v30
	v_mul_f32_e32 v13, v13, v31
	v_cvt_pk_bf16_f32 v12, v12, v13
	v_mul_f32_e32 v13, v22, v0
	v_mul_f32_e32 v13, v13, v32
	v_mul_f32_e32 v22, v23, v0
	v_mul_f32_e32 v22, v22, v33
	v_cvt_pk_bf16_f32 v13, v13, v22
	global_store_dwordx2 v[10:11], v[12:13], off offset:64
	v_mov_b64_e32 v[22:23], v[128:129]
	v_mov_b64_e32 v[24:25], v[130:131]
	v_mul_f32_e32 v12, v28, v0
	v_mul_f32_e32 v13, v29, v0
	v_mul_f32_e32 v12, v12, v22
	v_mul_f32_e32 v13, v13, v23
	v_cvt_pk_bf16_f32 v12, v12, v13
	v_mul_f32_e32 v13, v26, v0
	v_mul_f32_e32 v13, v13, v24
	v_mul_f32_e32 v22, v27, v0
	v_mul_f32_e32 v22, v22, v25
	v_cvt_pk_bf16_f32 v13, v13, v22
	global_store_dwordx2 v[10:11], v[12:13], off offset:96
	v_mov_b64_e32 v[22:23], v[132:133]
	v_mov_b64_e32 v[24:25], v[134:135]
	v_mul_f32_e32 v12, v16, v0
	v_mul_f32_e32 v13, v17, v0
	v_mul_f32_e32 v16, v20, v0
	v_mul_f32_e32 v12, v12, v22
	v_mul_f32_e32 v13, v13, v23
	v_cvt_pk_bf16_f32 v12, v12, v13
	v_mul_f32_e32 v13, v14, v0
	v_mul_f32_e32 v13, v13, v24
	v_mul_f32_e32 v14, v15, v0
	v_mul_f32_e32 v14, v14, v25
	v_cvt_pk_bf16_f32 v13, v13, v14
	global_store_dwordx2 v[10:11], v[12:13], off offset:128
	v_mov_b64_e32 v[12:13], v[136:137]
	v_mov_b64_e32 v[14:15], v[138:139]
	v_mul_f32_e32 v12, v16, v12
	v_mul_f32_e32 v16, v21, v0
	v_mul_f32_e32 v13, v16, v13
	v_cvt_pk_bf16_f32 v12, v12, v13
	v_mul_f32_e32 v13, v18, v0
	v_mul_f32_e32 v13, v13, v14
	v_mul_f32_e32 v14, v19, v0
	v_mul_f32_e32 v14, v14, v15
	v_cvt_pk_bf16_f32 v13, v13, v14
	global_store_dwordx2 v[10:11], v[12:13], off offset:160
	v_mov_b64_e32 v[12:13], v[140:141]
	v_mov_b64_e32 v[14:15], v[142:143]
	v_mul_f32_e32 v8, v8, v12
	v_mul_f32_e32 v9, v9, v13
	v_cvt_pk_bf16_f32 v8, v8, v9
	v_mul_f32_e32 v6, v6, v14
	v_mul_f32_e32 v7, v7, v15
	v_cvt_pk_bf16_f32 v9, v6, v7
	global_store_dwordx2 v[10:11], v[8:9], off offset:192
	v_mov_b64_e32 v[6:7], v[144:145]
	v_mov_b64_e32 v[8:9], v[146:147]
	v_mul_f32_e32 v2, v2, v6
	v_mul_f32_e32 v3, v3, v7
	v_cvt_pk_bf16_f32 v2, v2, v3
	v_mul_f32_e32 v3, v4, v0
	v_mul_f32_e32 v3, v3, v8
	v_mul_f32_e32 v0, v5, v0
	v_mul_f32_e32 v0, v0, v9
	v_cvt_pk_bf16_f32 v3, v3, v0
	global_store_dwordx2 v[10:11], v[2:3], off offset:224

; #define PG8_STAGE(bufoff, gbase, voff) do { _Pragma("unroll") for (int _i = 0; _i < 2; ++_i) \
;         __builtin_amdgcn_global_load_lds((const unsigned*)((const char*)(gbase) + (voff)[_i]), (LAS unsigned*)(lds + (bufoff) + ldsw + _i * 8192), 16, 0, 0); } while (0)
; #define PG8_LDA(dst, b, h) do { _Pragma("unroll") for (int m = 0; m < 4; ++m) _Pragma("unroll") for (int k = 0; k < 2; ++k) dst[m][k] = *(const LAS bf16x8*)(lds + PG8_SA(b, h) + aoff + m * 2048 + k * 1024); } while (0)
; #define PG8_LDB(dst, b, h) do { _Pragma("unroll") for (int n = 0; n < 2; ++n) _Pragma("unroll") for (int k = 0; k < 2; ++k) dst[n][k] = *(const LAS bf16x8*)(lds + PG8_SB(b, h) + boff + n * 2048 + k * 1024); } while (0)
; #define PG8_MMA(ai, bj, At, Bt) do { __builtin_amdgcn_s_setprio(1); _Pragma("unroll") for (int m = 0; m < 4; ++m) _Pragma("unroll") for (int n = 0; n < 2; ++n) _Pragma("unroll") for (int k = 0; k < 2; ++k) \
;         acc[ai][bj][m][n] = __builtin_amdgcn_mfma_f32_16x16x32_bf16(Bt[n][k], At[m][k], acc[ai][bj][m][n], 0, 0, 0); __builtin_amdgcn_s_setprio(0); } while (0)
; __device__ __forceinline__ void gemm_phase(LAS unsigned char* lds, const Params& p, const Sched& S, float alpha, const int TIDX) {
;     ...
;     f32x4 acc[2][2][4][2];
; #pragma unroll
;     for (int a = 0; a < 2; ++a)
; #pragma unroll
;         for (int b = 0; b < 2; ++b)
; #pragma unroll
;             for (int m = 0; m < 4; ++m)
; #pragma unroll
;                 for (int n = 0; n < 2; ++n) acc[a][b][m][n] = (f32x4){0.f, 0.f, 0.f, 0.f};
;     ...
;         for (int t = 0; t < nt; t += 2) {
;             const bool last = (t == nt - 2);
;             const char* a1 = cA + (size_t)(t + 1) * kstep;
;             const char* a2 = last ? nA : cA + (size_t)(t + 2) * kstep; const char* b2 = last ? nB : cB + (size_t)(t + 2) * kstep;
;             const char* a3 = a2 + kstep; const char* b3 = b2 + kstep;
;             PG8_LDB(B0, 0, 0); PG8_SCHED; PG8_LDA(At, 0, 0); PG8_STAGE(PG8_SA(1, 1), a1 + hstep, voffA);
;             PG8_WAIT_L(8); PG8_BAR; PG8_WAIT_L(0); PG8_MMA(0, 0, At, B0); PG8_BAR; PG8_SCHED;
;             PG8_LDB(B1, 0, 1); PG8_STAGE(PG8_SB(0, 0), b2, voffB);
;             PG8_BAR; PG8_WAIT_L(0); PG8_MMA(0, 1, At, B1); PG8_BAR;
;             PG8_LDA(At, 0, 1); PG8_STAGE(PG8_SA(0, 0), a2, voffA);
;             PG8_BAR; PG8_WAIT_L(0); PG8_MMA(1, 0, At, B0); PG8_BAR; PG8_SCHED;
.LBB0_287:
	s_cmp_lt_i32 s79, 1
	s_cbranch_scc1 .LBB0_290
	s_add_i32 s38, s79, -2
	s_add_u32 s6, s58, 0x80
	s_addc_u32 s7, s59, 0
	s_add_u32 s39, s60, 0x100
	s_addc_u32 s56, s61, 0
	s_mov_b32 s48, 0
	s_add_i32 s57, s48, 2
	s_add_u32 s50, s6, 0x80
	s_addc_u32 s49, s7, 0
	s_add_i32 s74, 0, 0x10000
	v_add_u32_e32 v0, s74, v200
	ds_read_b128 v[130:133], v0
	ds_read_b128 v[134:137], v0 offset:1024
	ds_read_b128 v[154:157], v0 offset:2048
	ds_read_b128 v[158:161], v0 offset:3072
	s_cmp_eq_u32 s38, s48
	s_cselect_b32 s48, s44, s50
	s_cselect_b32 s49, s45, s49
	s_cselect_b32 s51, s47, s56
	s_cselect_b32 s50, s46, s39
	v_lshl_add_u64 v[166:167], s[6:7], 0, v[150:151]
	s_add_i32 m0, s35, 0xc000
	ds_read_b128 v[162:165], v202
	ds_read_b128 v[170:173], v202 offset:1024
	ds_read_b128 v[174:177], v202 offset:2048
	ds_read_b128 v[178:181], v202 offset:3072
	ds_read_b128 v[182:185], v202 offset:4096
	ds_read_b128 v[204:207], v202 offset:5120
	ds_read_b128 v[208:211], v202 offset:6144
	ds_read_b128 v[212:215], v202 offset:7168
	global_load_lds_dwordx4 v[166:167], off
	v_lshl_add_u64 v[166:167], s[6:7], 0, v[152:153]
	s_add_i32 m0, s35, 0xe000
	s_nop 0
	global_load_lds_dwordx4 v[166:167], off
	s_waitcnt lgkmcnt(8)
	s_barrier
	s_waitcnt lgkmcnt(0)
	s_setprio 1
	s_waitcnt lgkmcnt(0)
	v_mfma_f32_16x16x32_bf16 v[126:129], v[130:133], v[162:165], 0
	v_mfma_f32_16x16x32_bf16 v[118:121], v[154:157], v[162:165], 0
	v_mfma_f32_16x16x32_bf16 v[110:113], v[130:133], v[174:177], 0
	v_mfma_f32_16x16x32_bf16 v[102:105], v[154:157], v[174:177], 0
	v_mfma_f32_16x16x32_bf16 v[94:97], v[130:133], v[182:185], 0
	v_mfma_f32_16x16x32_bf16 v[86:89], v[154:157], v[182:185], 0
	v_mfma_f32_16x16x32_bf16 v[78:81], v[130:133], v[208:211], 0
	v_mfma_f32_16x16x32_bf16 v[70:73], v[154:157], v[208:211], 0
	v_mfma_f32_16x16x32_bf16 v[126:129], v[134:137], v[170:173], v[126:129]
	v_mfma_f32_16x16x32_bf16 v[118:121], v[158:161], v[170:173], v[118:121]
	v_mfma_f32_16x16x32_bf16 v[110:113], v[134:137], v[178:181], v[110:113]
	v_mfma_f32_16x16x32_bf16 v[102:105], v[158:161], v[178:181], v[102:105]
	v_mfma_f32_16x16x32_bf16 v[94:97], v[134:137], v[204:207], v[94:97]
	v_mfma_f32_16x16x32_bf16 v[86:89], v[158:161], v[204:207], v[86:89]
	v_mfma_f32_16x16x32_bf16 v[78:81], v[134:137], v[212:215], v[78:81]
	v_mfma_f32_16x16x32_bf16 v[70:73], v[158:161], v[212:215], v[70:73]
	s_setprio 0
	s_barrier
	s_add_i32 s75, 0, 0x14000
	s_add_i32 s74, s74, s34
	v_add_u32_e32 v0, s75, v200
	v_lshl_add_u64 v[166:167], s[50:51], 0, v[140:141]
	s_mov_b32 m0, s74
	ds_read_b128 v[216:219], v0
	ds_read_b128 v[220:223], v0 offset:1024
	ds_read_b128 v[224:227], v0 offset:2048
	ds_read_b128 v[228:231], v0 offset:3072
	global_load_lds_dwordx4 v[166:167], off
	v_lshl_add_u64 v[186:187], s[50:51], 0, v[144:145]
	s_add_i32 m0, s74, 0x2000
	s_nop 0
	global_load_lds_dwordx4 v[186:187], off
	s_barrier
	s_waitcnt lgkmcnt(0)
	s_setprio 1
	s_waitcnt lgkmcnt(0)
	v_mfma_f32_16x16x32_bf16 v[122:125], v[216:219], v[162:165], 0
	v_mfma_f32_16x16x32_bf16 v[114:117], v[224:227], v[162:165], 0
	v_mfma_f32_16x16x32_bf16 v[106:109], v[216:219], v[174:177], 0
	v_mfma_f32_16x16x32_bf16 v[98:101], v[224:227], v[174:177], 0
	v_mfma_f32_16x16x32_bf16 v[90:93], v[216:219], v[182:185], 0
	v_mfma_f32_16x16x32_bf16 v[82:85], v[224:227], v[182:185], 0
	v_mfma_f32_16x16x32_bf16 v[74:77], v[216:219], v[208:211], 0
	v_mfma_f32_16x16x32_bf16 v[66:69], v[224:227], v[208:211], 0
	v_mfma_f32_16x16x32_bf16 v[122:125], v[220:223], v[170:173], v[122:125]
	v_mfma_f32_16x16x32_bf16 v[114:117], v[228:231], v[170:173], v[114:117]
	v_mfma_f32_16x16x32_bf16 v[106:109], v[220:223], v[178:181], v[106:109]
	v_mfma_f32_16x16x32_bf16 v[98:101], v[228:231], v[178:181], v[98:101]
	v_mfma_f32_16x16x32_bf16 v[90:93], v[220:223], v[204:207], v[90:93]
	v_mfma_f32_16x16x32_bf16 v[82:85], v[228:231], v[204:207], v[82:85]
	v_mfma_f32_16x16x32_bf16 v[74:77], v[220:223], v[212:215], v[74:77]
	v_mfma_f32_16x16x32_bf16 v[66:69], v[228:231], v[212:215], v[66:69]
	s_setprio 0
	s_mov_b32 m0, s35
	v_lshl_add_u64 v[232:233], s[48:49], 0, v[138:139]
	s_barrier
	ds_read_b128 v[162:165], v202 offset:16384
	ds_read_b128 v[170:173], v202 offset:17408
	ds_read_b128 v[174:177], v202 offset:18432
	ds_read_b128 v[178:181], v202 offset:19456
	ds_read_b128 v[182:185], v202 offset:20480
	ds_read_b128 v[204:207], v202 offset:21504
	ds_read_b128 v[208:211], v202 offset:22528
	ds_read_b128 v[212:215], v202 offset:23552
	global_load_lds_dwordx4 v[232:233], off
	v_lshl_add_u64 v[234:235], s[48:49], 0, v[142:143]
	s_mov_b32 m0, s36
	s_nop 0
	global_load_lds_dwordx4 v[234:235], off
	s_barrier
	s_waitcnt lgkmcnt(0)
	s_setprio 1
	s_waitcnt lgkmcnt(0)
	v_mfma_f32_16x16x32_bf16 v[62:65], v[130:133], v[162:165], 0
	v_mfma_f32_16x16x32_bf16 v[54:57], v[154:157], v[162:165], 0
	v_mfma_f32_16x16x32_bf16 v[46:49], v[130:133], v[174:177], 0
	v_mfma_f32_16x16x32_bf16 v[38:41], v[154:157], v[174:177], 0
	v_mfma_f32_16x16x32_bf16 v[30:33], v[130:133], v[182:185], 0
	v_mfma_f32_16x16x32_bf16 v[22:25], v[154:157], v[182:185], 0
	v_mfma_f32_16x16x32_bf16 v[14:17], v[130:133], v[208:211], 0
	v_mfma_f32_16x16x32_bf16 v[6:9], v[154:157], v[208:211], 0
	v_mfma_f32_16x16x32_bf16 v[62:65], v[134:137], v[170:173], v[62:65]
	v_mfma_f32_16x16x32_bf16 v[54:57], v[158:161], v[170:173], v[54:57]
	v_mfma_f32_16x16x32_bf16 v[46:49], v[134:137], v[178:181], v[46:49]
	v_mfma_f32_16x16x32_bf16 v[38:41], v[158:161], v[178:181], v[38:41]
	v_mfma_f32_16x16x32_bf16 v[30:33], v[134:137], v[204:207], v[30:33]
	v_mfma_f32_16x16x32_bf16 v[22:25], v[158:161], v[204:207], v[22:25]
	v_mfma_f32_16x16x32_bf16 v[14:17], v[134:137], v[212:215], v[14:17]
	v_mfma_f32_16x16x32_bf16 v[6:9], v[158:161], v[212:215], v[6:9]
	s_setprio 0
	s_barrier
; #define PG8_STAGE(bufoff, gbase, voff) do { _Pragma("unroll") for (int _i = 0; _i < 2; ++_i) \
;         __builtin_amdgcn_global_load_lds((const unsigned*)((const char*)(gbase) + (voff)[_i]), (LAS unsigned*)(lds + (bufoff) + ldsw + _i * 8192), 16, 0, 0); } while (0)
; #define PG8_LDA(dst, b, h) do { _Pragma("unroll") for (int m = 0; m < 4; ++m) _Pragma("unroll") for (int k = 0; k < 2; ++k) dst[m][k] = *(const LAS bf16x8*)(lds + PG8_SA(b, h) + aoff + m * 2048 + k * 1024); } while (0)
; #define PG8_LDB(dst, b, h) do { _Pragma("unroll") for (int n = 0; n < 2; ++n) _Pragma("unroll") for (int k = 0; k < 2; ++k) dst[n][k] = *(const LAS bf16x8*)(lds + PG8_SB(b, h) + boff + n * 2048 + k * 1024); } while (0)
; #define PG8_MMA(ai, bj, At, Bt) do { __builtin_amdgcn_s_setprio(1); _Pragma("unroll") for (int m = 0; m < 4; ++m) _Pragma("unroll") for (int n = 0; n < 2; ++n) _Pragma("unroll") for (int k = 0; k < 2; ++k) \
;         acc[ai][bj][m][n] = __builtin_amdgcn_mfma_f32_16x16x32_bf16(Bt[n][k], At[m][k], acc[ai][bj][m][n], 0, 0, 0); __builtin_amdgcn_s_setprio(0); } while (0)
; #define PG8_WAIT_V(n) asm volatile("s_waitcnt vmcnt(" #n ")" ::: "memory")
; #define PG8_WAIT_L(n) asm volatile("s_waitcnt lgkmcnt(" #n ")" ::: "memory")
; #define PG8_BAR __builtin_amdgcn_s_barrier()
; #define PG8_SCHED __builtin_amdgcn_sched_barrier(0)
; __device__ __forceinline__ void gemm_phase(LAS unsigned char* lds, const Params& p, const Sched& S, float alpha, const int TIDX) {
;     ...
;             PG8_STAGE(PG8_SB(0, 1), b2 + hstep, voffB);
;             PG8_WAIT_V(6); PG8_BAR; PG8_MMA(1, 1, At, B1); PG8_BAR;
;             PG8_LDB(B0, 1, 0); PG8_SCHED; PG8_LDA(At, 1, 0); PG8_STAGE(PG8_SA(0, 1), a2 + hstep, voffA);
;             PG8_WAIT_L(8); PG8_BAR; PG8_WAIT_L(0); PG8_MMA(0, 0, At, B0); PG8_BAR; PG8_SCHED;
;             PG8_LDB(B1, 1, 1); PG8_STAGE(PG8_SB(1, 0), b3, voffB);
;             PG8_BAR; PG8_WAIT_L(0); PG8_MMA(0, 1, At, B1); PG8_BAR;
	s_add_u32 s50, s50, s20
	s_addc_u32 s51, s51, 0
	s_add_i32 s74, s75, s34
	v_lshl_add_u64 v[236:237], s[50:51], 0, v[140:141]
	s_mov_b32 m0, s74
	v_lshl_add_u64 v[238:239], s[50:51], 0, v[144:145]
	global_load_lds_dwordx4 v[236:237], off
	s_add_i32 m0, s74, 0x2000
	s_nop 0
	global_load_lds_dwordx4 v[238:239], off
	s_waitcnt vmcnt(6)
	s_barrier
	s_setprio 1
	v_mfma_f32_16x16x32_bf16 v[58:61], v[216:219], v[162:165], 0
	v_mfma_f32_16x16x32_bf16 v[50:53], v[224:227], v[162:165], 0
	v_mfma_f32_16x16x32_bf16 v[42:45], v[216:219], v[174:177], 0
	v_mfma_f32_16x16x32_bf16 v[34:37], v[224:227], v[174:177], 0
	v_mfma_f32_16x16x32_bf16 v[26:29], v[216:219], v[182:185], 0
	v_mfma_f32_16x16x32_bf16 v[18:21], v[224:227], v[182:185], 0
	v_mfma_f32_16x16x32_bf16 v[10:13], v[216:219], v[208:211], 0
	v_mfma_f32_16x16x32_bf16 v[2:5], v[224:227], v[208:211], 0
	v_mfma_f32_16x16x32_bf16 v[58:61], v[220:223], v[170:173], v[58:61]
	v_mfma_f32_16x16x32_bf16 v[50:53], v[228:231], v[170:173], v[50:53]
	v_mfma_f32_16x16x32_bf16 v[42:45], v[220:223], v[178:181], v[42:45]
	v_mfma_f32_16x16x32_bf16 v[34:37], v[228:231], v[178:181], v[34:37]
	v_mfma_f32_16x16x32_bf16 v[26:29], v[220:223], v[204:207], v[26:29]
	v_mfma_f32_16x16x32_bf16 v[18:21], v[228:231], v[204:207], v[18:21]
	v_mfma_f32_16x16x32_bf16 v[10:13], v[220:223], v[212:215], v[10:13]
	v_mfma_f32_16x16x32_bf16 v[2:5], v[228:231], v[212:215], v[2:5]
	s_setprio 0
	s_add_i32 s50, 0, 0x18000
	v_add_u32_e32 v0, s50, v200
	s_barrier
	ds_read_b128 v[130:133], v0
	ds_read_b128 v[134:137], v0 offset:1024
	ds_read_b128 v[154:157], v0 offset:2048
	ds_read_b128 v[158:161], v0 offset:3072
	s_add_u32 s48, s48, s20
	s_addc_u32 s49, s49, 0
	s_mov_b32 m0, s37
	v_lshl_add_u64 v[216:217], s[48:49], 0, v[138:139]
	ds_read_b128 v[162:165], v202 offset:32768
	ds_read_b128 v[170:173], v202 offset:33792
	ds_read_b128 v[174:177], v202 offset:34816
	ds_read_b128 v[178:181], v202 offset:35840
	ds_read_b128 v[182:185], v202 offset:36864
	ds_read_b128 v[204:207], v202 offset:37888
	ds_read_b128 v[208:211], v202 offset:38912
	ds_read_b128 v[212:215], v202 offset:39936
	global_load_lds_dwordx4 v[216:217], off
	v_lshl_add_u64 v[216:217], s[48:49], 0, v[142:143]
	s_mov_b32 m0, s24
	s_nop 0
	global_load_lds_dwordx4 v[216:217], off
	s_waitcnt lgkmcnt(8)
	s_barrier
	s_waitcnt lgkmcnt(0)
	s_setprio 1
	s_waitcnt lgkmcnt(0)
	v_mfma_f32_16x16x32_bf16 v[126:129], v[130:133], v[162:165], v[126:129]
	v_mfma_f32_16x16x32_bf16 v[118:121], v[154:157], v[162:165], v[118:121]
	v_mfma_f32_16x16x32_bf16 v[110:113], v[130:133], v[174:177], v[110:113]
	v_mfma_f32_16x16x32_bf16 v[102:105], v[154:157], v[174:177], v[102:105]
	v_mfma_f32_16x16x32_bf16 v[94:97], v[130:133], v[182:185], v[94:97]
	v_mfma_f32_16x16x32_bf16 v[86:89], v[154:157], v[182:185], v[86:89]
	v_mfma_f32_16x16x32_bf16 v[78:81], v[130:133], v[208:211], v[78:81]
	v_mfma_f32_16x16x32_bf16 v[70:73], v[154:157], v[208:211], v[70:73]
	v_mfma_f32_16x16x32_bf16 v[126:129], v[134:137], v[170:173], v[126:129]
	v_mfma_f32_16x16x32_bf16 v[118:121], v[158:161], v[170:173], v[118:121]
	v_mfma_f32_16x16x32_bf16 v[110:113], v[134:137], v[178:181], v[110:113]
	v_mfma_f32_16x16x32_bf16 v[102:105], v[158:161], v[178:181], v[102:105]
	v_mfma_f32_16x16x32_bf16 v[94:97], v[134:137], v[204:207], v[94:97]
	v_mfma_f32_16x16x32_bf16 v[86:89], v[158:161], v[204:207], v[86:89]
	v_mfma_f32_16x16x32_bf16 v[78:81], v[134:137], v[212:215], v[78:81]
	v_mfma_f32_16x16x32_bf16 v[70:73], v[158:161], v[212:215], v[70:73]
	s_setprio 0
	s_barrier
	s_add_i32 s48, 0, 0x1c000
	s_add_i32 s49, s50, s34
	v_add_u32_e32 v0, s48, v200
	v_lshl_add_u64 v[166:167], v[166:167], 0, s[88:89]
	s_mov_b32 m0, s49
	ds_read_b128 v[216:219], v0
	ds_read_b128 v[220:223], v0 offset:1024
	ds_read_b128 v[224:227], v0 offset:2048
	ds_read_b128 v[228:231], v0 offset:3072
	global_load_lds_dwordx4 v[166:167], off
	v_lshl_add_u64 v[166:167], v[186:187], 0, s[88:89]
	s_add_i32 m0, s49, 0x2000
	s_nop 0
	global_load_lds_dwordx4 v[166:167], off
	s_barrier
; #define PG8_STAGE(bufoff, gbase, voff) do { _Pragma("unroll") for (int _i = 0; _i < 2; ++_i) \
;         __builtin_amdgcn_global_load_lds((const unsigned*)((const char*)(gbase) + (voff)[_i]), (LAS unsigned*)(lds + (bufoff) + ldsw + _i * 8192), 16, 0, 0); } while (0)
; #define PG8_LDA(dst, b, h) do { _Pragma("unroll") for (int m = 0; m < 4; ++m) _Pragma("unroll") for (int k = 0; k < 2; ++k) dst[m][k] = *(const LAS bf16x8*)(lds + PG8_SA(b, h) + aoff + m * 2048 + k * 1024); } while (0)
; #define PG8_MMA(ai, bj, At, Bt) do { __builtin_amdgcn_s_setprio(1); _Pragma("unroll") for (int m = 0; m < 4; ++m) _Pragma("unroll") for (int n = 0; n < 2; ++n) _Pragma("unroll") for (int k = 0; k < 2; ++k) \
;         acc[ai][bj][m][n] = __builtin_amdgcn_mfma_f32_16x16x32_bf16(Bt[n][k], At[m][k], acc[ai][bj][m][n], 0, 0, 0); __builtin_amdgcn_s_setprio(0); } while (0)
; #define PG8_WAIT_V(n) asm volatile("s_waitcnt vmcnt(" #n ")" ::: "memory")
; #define PG8_WAIT_L(n) asm volatile("s_waitcnt lgkmcnt(" #n ")" ::: "memory")
; #define PG8_BAR __builtin_amdgcn_s_barrier()
; #define PG8_SCHED __builtin_amdgcn_sched_barrier(0)
; __device__ __forceinline__ void gemm_phase(LAS unsigned char* lds, const Params& p, const Sched& S, float alpha, const int TIDX) {
;     ...
;             PG8_BAR; PG8_WAIT_L(0); PG8_MMA(0, 1, At, B1); PG8_BAR;
;             PG8_LDA(At, 1, 1); PG8_STAGE(PG8_SA(1, 0), a3, voffA);
;             PG8_BAR; PG8_WAIT_L(0); PG8_MMA(1, 0, At, B0); PG8_BAR; PG8_SCHED;
;             PG8_STAGE(PG8_SB(1, 1), b3 + hstep, voffB);
;             PG8_WAIT_V(6); PG8_BAR; PG8_MMA(1, 1, At, B1); PG8_BAR;
;         }
	s_waitcnt lgkmcnt(0)
	s_setprio 1
	s_waitcnt lgkmcnt(0)
	v_mfma_f32_16x16x32_bf16 v[122:125], v[216:219], v[162:165], v[122:125]
	v_mfma_f32_16x16x32_bf16 v[114:117], v[224:227], v[162:165], v[114:117]
	v_mfma_f32_16x16x32_bf16 v[106:109], v[216:219], v[174:177], v[106:109]
	v_mfma_f32_16x16x32_bf16 v[98:101], v[224:227], v[174:177], v[98:101]
	v_mfma_f32_16x16x32_bf16 v[90:93], v[216:219], v[182:185], v[90:93]
	v_mfma_f32_16x16x32_bf16 v[82:85], v[224:227], v[182:185], v[82:85]
	v_mfma_f32_16x16x32_bf16 v[74:77], v[216:219], v[208:211], v[74:77]
	v_mfma_f32_16x16x32_bf16 v[66:69], v[224:227], v[208:211], v[66:69]
	v_mfma_f32_16x16x32_bf16 v[122:125], v[220:223], v[170:173], v[122:125]
	v_mfma_f32_16x16x32_bf16 v[114:117], v[228:231], v[170:173], v[114:117]
	v_mfma_f32_16x16x32_bf16 v[106:109], v[220:223], v[178:181], v[106:109]
	v_mfma_f32_16x16x32_bf16 v[98:101], v[228:231], v[178:181], v[98:101]
	v_mfma_f32_16x16x32_bf16 v[90:93], v[220:223], v[204:207], v[90:93]
	v_mfma_f32_16x16x32_bf16 v[82:85], v[228:231], v[204:207], v[82:85]
	v_mfma_f32_16x16x32_bf16 v[74:77], v[220:223], v[212:215], v[74:77]
	v_mfma_f32_16x16x32_bf16 v[66:69], v[228:231], v[212:215], v[66:69]
	s_setprio 0
	s_mov_b32 m0, s25
	v_lshl_add_u64 v[166:167], v[232:233], 0, s[88:89]
	s_barrier
	ds_read_b128 v[162:165], v202 offset:49152
	ds_read_b128 v[170:173], v202 offset:50176
	ds_read_b128 v[174:177], v202 offset:51200
	ds_read_b128 v[178:181], v202 offset:52224
	ds_read_b128 v[182:185], v202 offset:53248
	ds_read_b128 v[204:207], v202 offset:54272
	ds_read_b128 v[208:211], v202 offset:55296
	ds_read_b128 v[212:215], v202 offset:56320
	global_load_lds_dwordx4 v[166:167], off
	v_lshl_add_u64 v[166:167], v[234:235], 0, s[88:89]
	s_mov_b32 m0, s68
	s_nop 0
	global_load_lds_dwordx4 v[166:167], off
	s_barrier
	s_waitcnt lgkmcnt(0)
	s_setprio 1
	s_waitcnt lgkmcnt(0)
	v_mfma_f32_16x16x32_bf16 v[62:65], v[130:133], v[162:165], v[62:65]
	v_mfma_f32_16x16x32_bf16 v[54:57], v[154:157], v[162:165], v[54:57]
	v_mfma_f32_16x16x32_bf16 v[46:49], v[130:133], v[174:177], v[46:49]
	v_mfma_f32_16x16x32_bf16 v[38:41], v[154:157], v[174:177], v[38:41]
	v_mfma_f32_16x16x32_bf16 v[30:33], v[130:133], v[182:185], v[30:33]
	v_mfma_f32_16x16x32_bf16 v[22:25], v[154:157], v[182:185], v[22:25]
	v_mfma_f32_16x16x32_bf16 v[14:17], v[130:133], v[208:211], v[14:17]
	v_mfma_f32_16x16x32_bf16 v[6:9], v[154:157], v[208:211], v[6:9]
	v_mfma_f32_16x16x32_bf16 v[62:65], v[134:137], v[170:173], v[62:65]
	v_mfma_f32_16x16x32_bf16 v[54:57], v[158:161], v[170:173], v[54:57]
	v_mfma_f32_16x16x32_bf16 v[46:49], v[134:137], v[178:181], v[46:49]
	v_mfma_f32_16x16x32_bf16 v[38:41], v[158:161], v[178:181], v[38:41]
	v_mfma_f32_16x16x32_bf16 v[30:33], v[134:137], v[204:207], v[30:33]
	v_mfma_f32_16x16x32_bf16 v[22:25], v[158:161], v[204:207], v[22:25]
	v_mfma_f32_16x16x32_bf16 v[14:17], v[134:137], v[212:215], v[14:17]
	v_mfma_f32_16x16x32_bf16 v[6:9], v[158:161], v[212:215], v[6:9]
	s_setprio 0
	s_barrier
	s_add_i32 s48, s48, s34
	v_lshl_add_u64 v[130:131], v[236:237], 0, s[88:89]
	s_mov_b32 m0, s48
	s_nop 0
	global_load_lds_dwordx4 v[130:131], off
	v_lshl_add_u64 v[130:131], v[238:239], 0, s[88:89]
	s_add_i32 m0, s48, 0x2000
	s_nop 0
	global_load_lds_dwordx4 v[130:131], off
	s_waitcnt vmcnt(6)
	s_barrier
	s_setprio 1
	v_mfma_f32_16x16x32_bf16 v[58:61], v[216:219], v[162:165], v[58:61]
	v_mfma_f32_16x16x32_bf16 v[50:53], v[224:227], v[162:165], v[50:53]
	v_mfma_f32_16x16x32_bf16 v[42:45], v[216:219], v[174:177], v[42:45]
	v_mfma_f32_16x16x32_bf16 v[34:37], v[224:227], v[174:177], v[34:37]
	v_mfma_f32_16x16x32_bf16 v[26:29], v[216:219], v[182:185], v[26:29]
	v_mfma_f32_16x16x32_bf16 v[18:21], v[224:227], v[182:185], v[18:21]
	v_mfma_f32_16x16x32_bf16 v[10:13], v[216:219], v[208:211], v[10:13]
	v_mfma_f32_16x16x32_bf16 v[2:5], v[224:227], v[208:211], v[2:5]
	v_mfma_f32_16x16x32_bf16 v[58:61], v[220:223], v[170:173], v[58:61]
	v_mfma_f32_16x16x32_bf16 v[50:53], v[228:231], v[170:173], v[50:53]
	v_mfma_f32_16x16x32_bf16 v[42:45], v[220:223], v[178:181], v[42:45]
	v_mfma_f32_16x16x32_bf16 v[34:37], v[228:231], v[178:181], v[34:37]
	v_mfma_f32_16x16x32_bf16 v[26:29], v[220:223], v[204:207], v[26:29]
	v_mfma_f32_16x16x32_bf16 v[18:21], v[228:231], v[204:207], v[18:21]
	v_mfma_f32_16x16x32_bf16 v[10:13], v[220:223], v[212:215], v[10:13]
	v_mfma_f32_16x16x32_bf16 v[2:5], v[228:231], v[212:215], v[2:5]
	s_setprio 0
	s_add_u32 s6, s6, 0x100
	s_addc_u32 s7, s7, 0
	s_add_u32 s39, s39, 0x100
	s_addc_u32 s56, s56, 0
	s_cmp_ge_i32 s57, s79
	s_mov_b32 s48, s57
	s_barrier
	s_cbranch_scc0 .LBB0_289
	s_branch .LBB0_291

; __device__ __forceinline__ void phase_prep0(const Params& p, unsigned char* sm, const int TIDX, const int BIDX) {
;     const int tid = TIDX, wid = tid >> 6, lane = tid & 63, wgid = BIDX * 8 + wid, nw = gridDim.x * 8;
;     float* scr = (float*)sm + wid * (64 * 33);
;     if (BIDX == 0 && tid == 0) { ((unsigned*)(p.ws + WS_CTL))[0] = 0u; }
;     for (int r = wgid; r < TT + 2048; r += nw) {
;         if (r < TT) norm_row_bf16(r < TP ? p.in[0] + (size_t)r * DM : p.in[1] + (size_t)(r - TP) * DM, p.in[9], (bf16_t*)(p.ws + WS_ABUF) + (size_t)r * DM, lane);
;         else norm_row_bf16(p.in[2] + (size_t)(r - TT) * DM, p.in[21], (bf16_t*)(p.ws + WS_AMEM) + (size_t)(r - TT) * DM, lane);
.LBB0_436:
	s_or_b64 exec, exec, s[4:5]
	v_ashrrev_i32_e32 v37, 6, v199
	v_readlane_b32 s3, v254, 41
	v_and_b32_e32 v36, 63, v199
	s_waitcnt lgkmcnt(0)
	s_lshl_b32 s4, s2, 3
	v_lshl_add_u32 v34, s3, 3, v37
	s_movk_i32 s3, 0x4a00
	v_cmp_gt_i32_e32 vcc, s3, v34
	s_and_saveexec_b64 s[6:7], vcc
	s_cbranch_execz .LBB0_445
	v_cmp_lt_i32_e32 vcc, v189, v188
	v_readlane_b32 s48, v255, 20
	v_readlane_b32 s49, v255, 21
	v_cndmask_b32_e32 v0, v169, v189, vcc
	v_cmp_lt_i32_e32 vcc, v190, v188
	v_lshlrev_b32_e32 v39, 2, v0
	v_readlane_b32 s50, v255, 22
	v_cndmask_b32_e32 v0, v169, v190, vcc
	v_cmp_lt_i32_e32 vcc, v191, v188
	v_lshlrev_b32_e32 v41, 2, v0
	v_readlane_b32 s51, v255, 23
	v_cndmask_b32_e32 v0, v169, v191, vcc
	v_cmp_lt_i32_e32 vcc, v192, v188
	v_lshlrev_b32_e32 v43, 2, v0
	v_readlane_b32 s52, v255, 24
	v_cndmask_b32_e32 v0, v169, v192, vcc
	v_cmp_lt_i32_e32 vcc, v193, v188
	v_readlane_b32 s53, v255, 25
	v_readlane_b32 s54, v255, 26
	v_readlane_b32 s55, v255, 27
	v_readlane_b32 s62, v255, 34
	v_readlane_b32 s63, v255, 35
	v_lshlrev_b32_e32 v45, 2, v0
	v_cndmask_b32_e32 v0, v169, v193, vcc
	v_cmp_lt_i32_e32 vcc, v194, v188
	s_mov_b64 s[14:15], s[62:63]
	v_readlane_b32 s48, v255, 12
	v_or_b32_e32 v38, 0x100, v36
	v_or_b32_e32 v40, 0x140, v36
	v_or_b32_e32 v42, 0x180, v36
	v_or_b32_e32 v44, 0x1c0, v36
	s_waitcnt vmcnt(0)
	v_lshlrev_b32_e32 v76, 2, v0
	v_cndmask_b32_e32 v0, v169, v194, vcc
	v_readlane_b32 s56, v255, 28
	v_readlane_b32 s57, v255, 29
	v_readlane_b32 s58, v255, 30
	v_readlane_b32 s59, v255, 31
	v_readlane_b32 s60, v255, 32
	v_readlane_b32 s61, v255, 33
	s_add_u32 s8, s14, 0xa484000
	v_readlane_b32 s49, v255, 13
	v_readlane_b32 s50, v255, 14
	v_readlane_b32 s51, v255, 15
	v_readlane_b32 s52, v255, 16
	v_readlane_b32 s53, v255, 17
	v_readlane_b32 s54, v255, 18
	v_readlane_b32 s55, v255, 19
	v_lshlrev_b32_e32 v77, 2, v0
	s_addc_u32 s9, s15, 0
	v_lshlrev_b32_e32 v0, 4, v36
	s_mov_b64 s[10:11], s[54:55]
	v_lshlrev_b32_e32 v2, 4, v38
	v_mov_b32_e32 v3, v1
	v_lshlrev_b32_e32 v4, 4, v40
	v_mov_b32_e32 v5, v1
	v_lshlrev_b32_e32 v6, 4, v42
	v_mov_b32_e32 v7, v1
	v_lshlrev_b32_e32 v8, 4, v44
	v_mov_b32_e32 v9, v1
	v_readlane_b32 s48, v254, 58
	v_lshl_add_u64 v[46:47], s[10:11], 0, v[0:1]
	v_lshl_add_u64 v[48:49], s[10:11], 0, v[2:3]
	v_lshl_add_u64 v[50:51], s[10:11], 0, v[4:5]
	v_lshl_add_u64 v[52:53], s[10:11], 0, v[6:7]
	v_lshl_add_u64 v[54:55], s[10:11], 0, v[8:9]
	s_add_u32 s10, s14, 0x6284000
	v_readlane_b32 s49, v254, 59
	v_readlane_b32 s50, v254, 60
	v_readlane_b32 s51, v254, 61
	v_readlane_b32 s52, v254, 62
	v_readlane_b32 s53, v254, 63
	v_readlane_b32 s54, v255, 0
	v_readlane_b32 s55, v255, 1
	v_readlane_b32 s56, v255, 2
	v_readlane_b32 s57, v255, 3
	v_readlane_b32 s58, v255, 4
	v_readlane_b32 s59, v255, 5
	v_readlane_b32 s60, v255, 6
	v_readlane_b32 s61, v255, 7
	v_readlane_b32 s62, v255, 8
	v_readlane_b32 s63, v255, 9
	s_addc_u32 s11, s15, 0
	s_mov_b64 s[14:15], s[50:51]
	v_ashrrev_i32_e32 v35, 31, v34
	v_readlane_b32 s48, v254, 42
	v_lshl_add_u64 v[58:59], s[14:15], 0, v[2:3]
	s_ashr_i32 s5, s4, 31
	v_lshlrev_b64 v[2:3], 13, v[34:35]
	v_readlane_b32 s49, v254, 43
	v_lshl_add_u64 v[56:57], s[14:15], 0, v[0:1]
	v_lshl_add_u64 v[60:61], s[14:15], 0, v[4:5]
	v_lshl_add_u64 v[62:63], s[14:15], 0, v[6:7]
	v_lshl_add_u64 v[64:65], s[14:15], 0, v[8:9]
	v_lshl_add_u64 v[66:67], s[48:49], 0, v[2:3]
	s_lshl_b64 s[12:13], s[4:5], 13
	s_mov_b64 s[14:15], 0
	v_mov_b64_e32 v[68:69], v[34:35]
	v_readlane_b32 s50, v254, 44
	v_readlane_b32 s51, v254, 45
	v_readlane_b32 s52, v254, 46
	v_readlane_b32 s53, v254, 47
	v_readlane_b32 s54, v254, 48
	v_readlane_b32 s55, v254, 49
	v_readlane_b32 s56, v254, 50
	v_readlane_b32 s57, v254, 51
	v_readlane_b32 s58, v254, 52
	v_readlane_b32 s59, v254, 53
	v_readlane_b32 s60, v254, 54
	v_readlane_b32 s61, v254, 55
	v_readlane_b32 s62, v254, 56
	v_readlane_b32 s63, v254, 57
	global_load_dwordx4 v[204:207], v[56:57], off
	global_load_dwordx4 v[208:211], v[56:57], off offset:1024
	global_load_dwordx4 v[212:215], v[56:57], off offset:2048
	global_load_dwordx4 v[216:219], v[56:57], off offset:3072
	global_load_dwordx4 v[220:223], v[58:59], off
	global_load_dwordx4 v[224:227], v[60:61], off
	global_load_dwordx4 v[228:231], v[62:63], off
	global_load_dwordx4 v[232:235], v[64:65], off
	global_load_dwordx4 v[86:89], v[46:47], off
	global_load_dwordx4 v[90:93], v[46:47], off offset:1024
	global_load_dwordx4 v[94:97], v[46:47], off offset:2048
	global_load_dwordx4 v[98:101], v[46:47], off offset:3072
	global_load_dwordx4 v[102:105], v[48:49], off
	global_load_dwordx4 v[106:109], v[50:51], off
	global_load_dwordx4 v[110:113], v[52:53], off
	global_load_dwordx4 v[114:117], v[54:55], off
	s_waitcnt vmcnt(0)
	s_branch .LBB0_440
; __device__ __forceinline__ unsigned pk2(float lo, float hi) { unsigned r; asm("v_cvt_pk_bf16_f32 %0, %1, %2" : "=v"(r) : "v"(lo), "v"(hi)); return r; }
; __device__ __forceinline__ void norm_row_bf16(const float* __restrict__ x, const float* __restrict__ g, bf16_t* __restrict__ o, int lane) {
;     f32x4 v[8]; float s = 0.f;
; #pragma unroll
;     for (int j = 0; j < 8; ++j) { v[j] = ((const f32x4*)x)[j * 64 + lane]; s += v[j][0] * v[j][0] + v[j][1] * v[j][1] + v[j][2] * v[j][2] + v[j][3] * v[j][3]; }
;     s = wave_sum(s); const float rs = rsqrtf(s * (1.0f / DM) + EPS);
; #pragma unroll
;     for (int j = 0; j < 8; ++j) { const f32x4 gg = ((const f32x4*)g)[j * 64 + lane]; u32x2 w; w.x = pk2(v[j][0] * rs * gg[0], v[j][1] * rs * gg[1]); w.y = pk2(v[j][2] * rs * gg[2], v[j][3] * rs * gg[3]); ((u32x2*)o)[j * 64 + lane] = w; }
; }
.LBB0_438:
	s_or_b64 exec, exec, s[18:19]
	v_lshlrev_b64 v[10:11], 12, v[10:11]
	v_lshl_add_u64 v[72:73], s[10:11], 0, v[10:11]
	v_lshl_add_u64 v[10:11], v[74:75], 0, v[0:1]
	global_load_dwordx4 v[30:33], v[10:11], off
	global_load_dwordx4 v[26:29], v[10:11], off offset:1024
	global_load_dwordx4 v[22:25], v[10:11], off offset:2048
	global_load_dwordx4 v[18:21], v[10:11], off offset:3072
	v_mov_b32_e32 v9, v1
	v_mov_b32_e32 v7, v1
	v_lshl_add_u64 v[8:9], v[74:75], 0, v[8:9]
	v_lshl_add_u64 v[6:7], v[74:75], 0, v[6:7]
	global_load_dwordx4 v[14:17], v[8:9], off
	v_mov_b32_e32 v5, v1
	global_load_dwordx4 v[6:9], v[6:7], off
	v_lshl_add_u64 v[4:5], v[74:75], 0, v[4:5]
	v_mov_b32_e32 v71, v1
	s_waitcnt vmcnt(5)
	v_mul_f32_e32 v0, v31, v31
	s_waitcnt vmcnt(4)
	v_mul_f32_e32 v3, v27, v27
	v_fmac_f32_e32 v0, v30, v30
	v_fmac_f32_e32 v3, v26, v26
	v_fmac_f32_e32 v0, v32, v32
	v_fmac_f32_e32 v3, v28, v28
	v_fmac_f32_e32 v0, v33, v33
	v_fmac_f32_e32 v3, v29, v29
	v_add_f32_e32 v0, v0, v3
	s_waitcnt vmcnt(3)
	v_mul_f32_e32 v3, v23, v23
	v_fmac_f32_e32 v3, v22, v22
	v_fmac_f32_e32 v3, v24, v24
	v_fmac_f32_e32 v3, v25, v25
	v_add_f32_e32 v0, v0, v3
	s_waitcnt vmcnt(2)
	v_mul_f32_e32 v3, v19, v19
	s_waitcnt vmcnt(1)
	v_mov_b32_e32 v12, v15
	s_waitcnt vmcnt(0)
	v_mov_b32_e32 v13, v7
	v_fmac_f32_e32 v3, v18, v18
	v_mov_b32_e32 v10, v14
	v_mov_b32_e32 v11, v6
	v_pk_mul_f32 v[12:13], v[12:13], v[12:13]
	v_fmac_f32_e32 v3, v20, v20
	v_pk_fma_f32 v[10:11], v[10:11], v[10:11], v[12:13]
	v_mov_b32_e32 v12, v16
	v_mov_b32_e32 v13, v8
	v_fmac_f32_e32 v3, v21, v21
	v_pk_fma_f32 v[10:11], v[12:13], v[12:13], v[10:11]
	v_mov_b32_e32 v12, v17
	v_mov_b32_e32 v13, v9
	v_add_f32_e32 v0, v0, v3
	v_pk_fma_f32 v[10:11], v[12:13], v[12:13], v[10:11]
	v_mov_b32_e32 v3, v1
	v_add_f32_e32 v0, v0, v10
	v_lshl_add_u64 v[2:3], v[74:75], 0, v[2:3]
	v_add_f32_e32 v0, v0, v11
	global_load_dwordx4 v[10:13], v[4:5], off
	s_waitcnt vmcnt(0)
	v_mov_b32_e32 v78, v11
	global_load_dwordx4 v[2:5], v[2:3], off
	v_mov_b32_e32 v74, v10
	s_waitcnt vmcnt(0)
	v_mov_b32_e32 v79, v3
	v_mov_b32_e32 v75, v2
	v_pk_mul_f32 v[78:79], v[78:79], v[78:79]
	s_nop 0
	v_pk_fma_f32 v[74:75], v[74:75], v[74:75], v[78:79]
	v_mov_b32_e32 v78, v12
	v_mov_b32_e32 v79, v4
	v_pk_fma_f32 v[74:75], v[78:79], v[78:79], v[74:75]
	v_mov_b32_e32 v78, v13
	v_mov_b32_e32 v79, v5
	v_pk_fma_f32 v[74:75], v[78:79], v[78:79], v[74:75]
	v_mov_b64_e32 v[78:79], v[204:205]
	v_mov_b64_e32 v[80:81], v[206:207]
	v_add_f32_e32 v0, v0, v74
	v_add_f32_e32 v0, v0, v75
	ds_bpermute_b32 v35, v39, v0
	s_waitcnt lgkmcnt(0)
	v_add_f32_e32 v0, v0, v35
	ds_bpermute_b32 v35, v41, v0
	s_waitcnt lgkmcnt(0)
	v_add_f32_e32 v0, v0, v35
	ds_bpermute_b32 v35, v43, v0
	s_waitcnt lgkmcnt(0)
	v_add_f32_e32 v0, v0, v35
	ds_bpermute_b32 v35, v45, v0
	s_waitcnt lgkmcnt(0)
	v_add_f32_e32 v0, v0, v35
	ds_bpermute_b32 v35, v76, v0
	s_waitcnt lgkmcnt(0)
	v_add_f32_e32 v0, v0, v35
	ds_bpermute_b32 v35, v77, v0
	s_waitcnt lgkmcnt(0)
	v_add_f32_e32 v0, v0, v35
	v_fmamk_f32 v0, v0, 0x3a000000, v168
	v_cmp_gt_f32_e32 vcc, s97, v0
	v_mul_f32_e32 v35, 0x4b800000, v0
	s_nop 0
	v_cndmask_b32_e32 v0, v0, v35, vcc
	v_rsq_f32_e32 v0, v0
	s_nop 0
	v_mul_f32_e32 v35, 0x45800000, v0
	v_cndmask_b32_e32 v0, v0, v35, vcc
	v_mul_f32_e32 v30, v30, v0
	v_mul_f32_e32 v31, v31, v0
	v_mul_f32_e32 v26, v26, v0
	v_mul_f32_e32 v27, v27, v0
	v_mul_f32_e32 v22, v22, v0
	v_mul_f32_e32 v23, v23, v0
	v_mul_f32_e32 v18, v18, v0
	v_mul_f32_e32 v19, v19, v0
	v_mul_f32_e32 v14, v14, v0
	v_mul_f32_e32 v15, v15, v0
	v_mul_f32_e32 v6, v6, v0
	v_mul_f32_e32 v7, v7, v0
	v_mul_f32_e32 v10, v10, v0
	v_mul_f32_e32 v2, v2, v0
	v_mul_f32_e32 v3, v3, v0
	v_mul_f32_e32 v30, v78, v30
	v_mul_f32_e32 v31, v79, v31
	v_cvt_pk_bf16_f32 v74, v30, v31
	v_mul_f32_e32 v30, v32, v0
	v_mul_f32_e32 v31, v33, v0
	v_mul_f32_e32 v30, v80, v30
	v_mul_f32_e32 v31, v81, v31
	v_mov_b64_e32 v[78:79], v[208:209]
	v_mov_b64_e32 v[80:81], v[210:211]
	v_cvt_pk_bf16_f32 v75, v30, v31
	v_lshl_add_u64 v[30:31], v[72:73], 0, v[70:71]
	global_store_dwordx2 v[30:31], v[74:75], off
	s_waitcnt vmcnt(1)
	v_mul_f32_e32 v26, v78, v26
	v_mul_f32_e32 v27, v79, v27
	v_cvt_pk_bf16_f32 v26, v26, v27
	v_mul_f32_e32 v27, v28, v0
	v_mul_f32_e32 v27, v80, v27
	v_mul_f32_e32 v28, v29, v0
	v_mul_f32_e32 v28, v81, v28
	v_cvt_pk_bf16_f32 v27, v27, v28
	global_store_dwordx2 v[30:31], v[26:27], off offset:512
	v_mov_b64_e32 v[26:27], v[212:213]
	v_mov_b64_e32 v[28:29], v[214:215]
	v_mul_f32_e32 v22, v26, v22
	v_mul_f32_e32 v23, v27, v23
	v_cvt_pk_bf16_f32 v22, v22, v23
	v_mul_f32_e32 v23, v24, v0
	v_mul_f32_e32 v23, v28, v23
	v_mul_f32_e32 v24, v25, v0
	v_mul_f32_e32 v24, v29, v24
	v_cvt_pk_bf16_f32 v23, v23, v24
	global_store_dwordx2 v[30:31], v[22:23], off offset:1024
	v_mov_b64_e32 v[22:23], v[216:217]
	v_mov_b64_e32 v[24:25], v[218:219]
	v_mul_f32_e32 v18, v18, v22
	v_mul_f32_e32 v19, v19, v23
	v_cvt_pk_bf16_f32 v18, v18, v19
	v_mul_f32_e32 v19, v20, v0
	v_mul_f32_e32 v19, v19, v24
	v_mul_f32_e32 v20, v21, v0
	v_mul_f32_e32 v20, v20, v25
	v_cvt_pk_bf16_f32 v19, v19, v20
	global_store_dwordx2 v[30:31], v[18:19], off offset:1536
	v_mov_b64_e32 v[18:19], v[220:221]
	v_mov_b64_e32 v[20:21], v[222:223]
	v_mul_f32_e32 v14, v14, v18
	v_mul_f32_e32 v15, v15, v19
	v_cvt_pk_bf16_f32 v14, v14, v15
	v_mul_f32_e32 v15, v16, v0
	v_mul_f32_e32 v15, v15, v20
	v_mul_f32_e32 v16, v17, v0
	v_mul_f32_e32 v16, v16, v21
	v_cvt_pk_bf16_f32 v15, v15, v16
	global_store_dwordx2 v[30:31], v[14:15], off offset:2048
	v_mov_b64_e32 v[14:15], v[224:225]
	v_mov_b64_e32 v[16:17], v[226:227]
	v_mul_f32_e32 v6, v6, v14
	v_mul_f32_e32 v7, v7, v15
	v_cvt_pk_bf16_f32 v6, v6, v7
	v_mul_f32_e32 v7, v8, v0
	v_mul_f32_e32 v7, v7, v16
	v_mul_f32_e32 v8, v9, v0
	v_mul_f32_e32 v8, v8, v17
	v_cvt_pk_bf16_f32 v7, v7, v8
	global_store_dwordx2 v[30:31], v[6:7], off offset:2560
	v_mov_b64_e32 v[6:7], v[228:229]
	v_mov_b64_e32 v[8:9], v[230:231]
	v_mul_f32_e32 v6, v10, v6
	v_mul_f32_e32 v10, v11, v0
	v_mul_f32_e32 v7, v10, v7
	v_cvt_pk_bf16_f32 v6, v6, v7
	v_mul_f32_e32 v7, v12, v0
	v_mul_f32_e32 v7, v7, v8
	v_mul_f32_e32 v8, v13, v0
	v_mul_f32_e32 v8, v8, v9
	v_cvt_pk_bf16_f32 v7, v7, v8
	global_store_dwordx2 v[30:31], v[6:7], off offset:3072
	v_mov_b64_e32 v[6:7], v[232:233]
	v_mov_b64_e32 v[8:9], v[234:235]
	v_mul_f32_e32 v2, v2, v6
	v_mul_f32_e32 v3, v3, v7
	v_cvt_pk_bf16_f32 v10, v2, v3
	v_mul_f32_e32 v2, v4, v0
	v_mul_f32_e32 v0, v5, v0
	v_mul_f32_e32 v2, v2, v8
	v_mul_f32_e32 v0, v0, v9
	v_cvt_pk_bf16_f32 v11, v2, v0

; __device__ __forceinline__ void phase_prep0(const Params& p, unsigned char* sm, const int TIDX, const int BIDX) {
;     ...
;     for (int r = wgid; r < TT + 2048; r += nw) {
;         if (r < TT) norm_row_bf16(r < TP ? p.in[0] + (size_t)r * DM : p.in[1] + (size_t)(r - TP) * DM, p.in[9], (bf16_t*)(p.ws + WS_ABUF) + (size_t)r * DM, lane);
;         else norm_row_bf16(p.in[2] + (size_t)(r - TT) * DM, p.in[21], (bf16_t*)(p.ws + WS_AMEM) + (size_t)(r - TT) * DM, lane);
.LBB0_440:
	s_movk_i32 s3, 0x41ff
	v_cmp_lt_i32_e32 vcc, s3, v68
	v_lshlrev_b32_e32 v0, 4, v36
	v_lshlrev_b32_e32 v8, 4, v38
	v_lshlrev_b32_e32 v6, 4, v40
	v_lshlrev_b32_e32 v4, 4, v42
	v_lshlrev_b32_e32 v2, 4, v44
	v_lshlrev_b32_e32 v70, 3, v36
	s_and_saveexec_b64 s[16:17], vcc
	s_xor_b64 s[16:17], exec, s[16:17]
	s_cbranch_execz .LBB0_442
; __device__ __forceinline__ unsigned pk2(float lo, float hi) { unsigned r; asm("v_cvt_pk_bf16_f32 %0, %1, %2" : "=v"(r) : "v"(lo), "v"(hi)); return r; }
; __device__ __forceinline__ void norm_row_bf16(const float* __restrict__ x, const float* __restrict__ g, bf16_t* __restrict__ o, int lane) {
;     f32x4 v[8]; float s = 0.f;
; #pragma unroll
;     for (int j = 0; j < 8; ++j) { v[j] = ((const f32x4*)x)[j * 64 + lane]; s += v[j][0] * v[j][0] + v[j][1] * v[j][1] + v[j][2] * v[j][2] + v[j][3] * v[j][3]; }
;     s = wave_sum(s); const float rs = rsqrtf(s * (1.0f / DM) + EPS);
; #pragma unroll
;     for (int j = 0; j < 8; ++j) { const f32x4 gg = ((const f32x4*)g)[j * 64 + lane]; u32x2 w; w.x = pk2(v[j][0] * rs * gg[0], v[j][1] * rs * gg[1]); w.y = pk2(v[j][2] * rs * gg[2], v[j][3] * rs * gg[3]); ((u32x2*)o)[j * 64 + lane] = w; }
; }
; __device__ __forceinline__ void phase_prep0(const Params& p, unsigned char* sm, const int TIDX, const int BIDX) {
;     ...
;         else norm_row_bf16(p.in[2] + (size_t)(r - TT) * DM, p.in[21], (bf16_t*)(p.ws + WS_AMEM) + (size_t)(r - TT) * DM, lane);
	v_add_u32_e32 v10, 0xffffbe00, v68
	v_mov_b32_e32 v11, v1
	v_readlane_b32 s48, v254, 42
	v_lshlrev_b64 v[12:13], 13, v[10:11]
	v_readlane_b32 s52, v254, 46
	v_readlane_b32 s53, v254, 47
	v_lshlrev_b64 v[10:11], 12, v[10:11]
	v_lshl_add_u64 v[72:73], s[8:9], 0, v[10:11]
	v_lshl_add_u64 v[74:75], s[52:53], 0, v[12:13]
	v_lshl_add_u64 v[10:11], v[74:75], 0, v[0:1]
	global_load_dwordx4 v[30:33], v[10:11], off
	global_load_dwordx4 v[26:29], v[10:11], off offset:1024
	global_load_dwordx4 v[22:25], v[10:11], off offset:2048
	global_load_dwordx4 v[18:21], v[10:11], off offset:3072
	v_mov_b32_e32 v9, v1
	v_mov_b32_e32 v7, v1
	v_lshl_add_u64 v[8:9], v[74:75], 0, v[8:9]
	v_lshl_add_u64 v[6:7], v[74:75], 0, v[6:7]
	global_load_dwordx4 v[14:17], v[8:9], off
	v_mov_b32_e32 v5, v1
	global_load_dwordx4 v[6:9], v[6:7], off
	v_lshl_add_u64 v[4:5], v[74:75], 0, v[4:5]
	v_mov_b32_e32 v71, v1
	v_readlane_b32 s49, v254, 43
	v_readlane_b32 s50, v254, 44
	v_readlane_b32 s51, v254, 45
	v_readlane_b32 s54, v254, 48
	v_readlane_b32 s55, v254, 49
	v_readlane_b32 s56, v254, 50
	v_readlane_b32 s57, v254, 51
	v_readlane_b32 s58, v254, 52
	v_readlane_b32 s59, v254, 53
	v_readlane_b32 s60, v254, 54
	v_readlane_b32 s61, v254, 55
	v_readlane_b32 s62, v254, 56
	v_readlane_b32 s63, v254, 57
	s_waitcnt vmcnt(5)
	v_mul_f32_e32 v0, v31, v31
	s_waitcnt vmcnt(4)
	v_mul_f32_e32 v3, v27, v27
	v_fmac_f32_e32 v0, v30, v30
	v_fmac_f32_e32 v3, v26, v26
	v_fmac_f32_e32 v0, v32, v32
	v_fmac_f32_e32 v3, v28, v28
	v_fmac_f32_e32 v0, v33, v33
	v_fmac_f32_e32 v3, v29, v29
	v_add_f32_e32 v0, v0, v3
	s_waitcnt vmcnt(3)
	v_mul_f32_e32 v3, v23, v23
	v_fmac_f32_e32 v3, v22, v22
	v_fmac_f32_e32 v3, v24, v24
	v_fmac_f32_e32 v3, v25, v25
	v_add_f32_e32 v0, v0, v3
	s_waitcnt vmcnt(2)
	v_mul_f32_e32 v3, v19, v19
	s_waitcnt vmcnt(1)
	v_mov_b32_e32 v12, v15
	s_waitcnt vmcnt(0)
	v_mov_b32_e32 v13, v7
	v_fmac_f32_e32 v3, v18, v18
	v_mov_b32_e32 v10, v14
	v_mov_b32_e32 v11, v6
	v_pk_mul_f32 v[12:13], v[12:13], v[12:13]
	v_fmac_f32_e32 v3, v20, v20
	v_pk_fma_f32 v[10:11], v[10:11], v[10:11], v[12:13]
	v_mov_b32_e32 v12, v16
	v_mov_b32_e32 v13, v8
	v_fmac_f32_e32 v3, v21, v21
	v_pk_fma_f32 v[10:11], v[12:13], v[12:13], v[10:11]
	v_mov_b32_e32 v12, v17
	v_mov_b32_e32 v13, v9
	v_add_f32_e32 v0, v0, v3
	v_pk_fma_f32 v[10:11], v[12:13], v[12:13], v[10:11]
	v_mov_b32_e32 v3, v1
	v_add_f32_e32 v0, v0, v10
	v_lshl_add_u64 v[2:3], v[74:75], 0, v[2:3]
	v_add_f32_e32 v0, v0, v11
	global_load_dwordx4 v[10:13], v[4:5], off
	s_waitcnt vmcnt(0)
	v_mov_b32_e32 v78, v11
	global_load_dwordx4 v[2:5], v[2:3], off
	v_mov_b32_e32 v74, v10
	s_waitcnt vmcnt(0)
	v_mov_b32_e32 v79, v3
	v_mov_b32_e32 v75, v2
	v_pk_mul_f32 v[78:79], v[78:79], v[78:79]
	s_nop 0
	v_pk_fma_f32 v[74:75], v[74:75], v[74:75], v[78:79]
	v_mov_b32_e32 v78, v12
	v_mov_b32_e32 v79, v4
	v_pk_fma_f32 v[74:75], v[78:79], v[78:79], v[74:75]
	v_mov_b32_e32 v78, v13
	v_mov_b32_e32 v79, v5
	v_pk_fma_f32 v[74:75], v[78:79], v[78:79], v[74:75]
	v_mov_b64_e32 v[78:79], v[86:87]
	v_mov_b64_e32 v[80:81], v[88:89]
	v_add_f32_e32 v0, v0, v74
	v_add_f32_e32 v0, v0, v75
	ds_bpermute_b32 v35, v39, v0
	s_waitcnt lgkmcnt(0)
	v_add_f32_e32 v0, v0, v35
	ds_bpermute_b32 v35, v41, v0
	s_waitcnt lgkmcnt(0)
	v_add_f32_e32 v0, v0, v35
	ds_bpermute_b32 v35, v43, v0
	s_waitcnt lgkmcnt(0)
	v_add_f32_e32 v0, v0, v35
	ds_bpermute_b32 v35, v45, v0
	s_waitcnt lgkmcnt(0)
	v_add_f32_e32 v0, v0, v35
	ds_bpermute_b32 v35, v76, v0
	s_waitcnt lgkmcnt(0)
	v_add_f32_e32 v0, v0, v35
	ds_bpermute_b32 v35, v77, v0
	s_waitcnt lgkmcnt(0)
	v_add_f32_e32 v0, v0, v35
	v_fmamk_f32 v0, v0, 0x3a000000, v168
	v_cmp_gt_f32_e32 vcc, s97, v0
	v_mul_f32_e32 v35, 0x4b800000, v0
	s_nop 0
	v_cndmask_b32_e32 v0, v0, v35, vcc
	v_rsq_f32_e32 v0, v0
	s_nop 0
	v_mul_f32_e32 v35, 0x45800000, v0
	v_cndmask_b32_e32 v0, v0, v35, vcc
	v_mul_f32_e32 v30, v30, v0
	v_mul_f32_e32 v31, v31, v0
	v_mul_f32_e32 v26, v26, v0
	v_mul_f32_e32 v27, v27, v0
	v_mul_f32_e32 v22, v22, v0
	v_mul_f32_e32 v23, v23, v0
	v_mul_f32_e32 v18, v18, v0
	v_mul_f32_e32 v19, v19, v0
	v_mul_f32_e32 v14, v14, v0
	v_mul_f32_e32 v15, v15, v0
	v_mul_f32_e32 v6, v6, v0
	v_mul_f32_e32 v7, v7, v0
	v_mul_f32_e32 v10, v10, v0
	v_mul_f32_e32 v2, v2, v0
	v_mul_f32_e32 v3, v3, v0
	v_mul_f32_e32 v30, v78, v30
	v_mul_f32_e32 v31, v79, v31
	v_cvt_pk_bf16_f32 v74, v30, v31
	v_mul_f32_e32 v30, v32, v0
	v_mul_f32_e32 v31, v33, v0
	v_mul_f32_e32 v30, v80, v30
	v_mul_f32_e32 v31, v81, v31
	v_mov_b64_e32 v[78:79], v[90:91]
	v_mov_b64_e32 v[80:81], v[92:93]
	v_cvt_pk_bf16_f32 v75, v30, v31
	v_lshl_add_u64 v[30:31], v[72:73], 0, v[70:71]
	global_store_dwordx2 v[30:31], v[74:75], off
	s_waitcnt vmcnt(1)
	v_mul_f32_e32 v26, v78, v26
	v_mul_f32_e32 v27, v79, v27
	v_cvt_pk_bf16_f32 v26, v26, v27
	v_mul_f32_e32 v27, v28, v0
	v_mul_f32_e32 v27, v80, v27
	v_mul_f32_e32 v28, v29, v0
	v_mul_f32_e32 v28, v81, v28
	v_cvt_pk_bf16_f32 v27, v27, v28
	global_store_dwordx2 v[30:31], v[26:27], off offset:512
	v_mov_b64_e32 v[26:27], v[94:95]
	v_mov_b64_e32 v[28:29], v[96:97]
	v_mul_f32_e32 v22, v26, v22
	v_mul_f32_e32 v23, v27, v23
	v_cvt_pk_bf16_f32 v22, v22, v23
	v_mul_f32_e32 v23, v24, v0
	v_mul_f32_e32 v23, v28, v23
	v_mul_f32_e32 v24, v25, v0
	v_mul_f32_e32 v24, v29, v24
	v_cvt_pk_bf16_f32 v23, v23, v24
	global_store_dwordx2 v[30:31], v[22:23], off offset:1024
	v_mov_b64_e32 v[22:23], v[98:99]
	v_mov_b64_e32 v[24:25], v[100:101]
	v_mul_f32_e32 v18, v18, v22
	v_mul_f32_e32 v19, v19, v23
	v_cvt_pk_bf16_f32 v18, v18, v19
	v_mul_f32_e32 v19, v20, v0
	v_mul_f32_e32 v19, v19, v24
	v_mul_f32_e32 v20, v21, v0
	v_mul_f32_e32 v20, v20, v25
	v_cvt_pk_bf16_f32 v19, v19, v20
	global_store_dwordx2 v[30:31], v[18:19], off offset:1536
	v_mov_b64_e32 v[18:19], v[102:103]
	v_mov_b64_e32 v[20:21], v[104:105]
	v_mul_f32_e32 v14, v14, v18
	v_mul_f32_e32 v15, v15, v19
	v_cvt_pk_bf16_f32 v14, v14, v15
	v_mul_f32_e32 v15, v16, v0
	v_mul_f32_e32 v15, v15, v20
	v_mul_f32_e32 v16, v17, v0
	v_mul_f32_e32 v16, v16, v21
	v_cvt_pk_bf16_f32 v15, v15, v16
	global_store_dwordx2 v[30:31], v[14:15], off offset:2048
	v_mov_b64_e32 v[14:15], v[106:107]
	v_mov_b64_e32 v[16:17], v[108:109]
	v_mul_f32_e32 v6, v6, v14
	v_mul_f32_e32 v7, v7, v15
	v_cvt_pk_bf16_f32 v6, v6, v7
	v_mul_f32_e32 v7, v8, v0
	v_mul_f32_e32 v7, v7, v16
	v_mul_f32_e32 v8, v9, v0
	v_mul_f32_e32 v8, v8, v17
	v_cvt_pk_bf16_f32 v7, v7, v8
	global_store_dwordx2 v[30:31], v[6:7], off offset:2560
	v_mov_b64_e32 v[6:7], v[110:111]
	v_mov_b64_e32 v[8:9], v[112:113]
	v_mul_f32_e32 v6, v10, v6
	v_mul_f32_e32 v10, v11, v0
	v_mul_f32_e32 v7, v10, v7
	v_cvt_pk_bf16_f32 v6, v6, v7
	v_mul_f32_e32 v7, v12, v0
	v_mul_f32_e32 v7, v7, v8
	v_mul_f32_e32 v8, v13, v0
	v_mul_f32_e32 v8, v8, v9
	v_cvt_pk_bf16_f32 v7, v7, v8
	global_store_dwordx2 v[30:31], v[6:7], off offset:3072
	v_mov_b64_e32 v[6:7], v[114:115]
	v_mov_b64_e32 v[8:9], v[116:117]
	v_mul_f32_e32 v2, v2, v6
	v_mul_f32_e32 v3, v3, v7
	v_cvt_pk_bf16_f32 v10, v2, v3
	v_mul_f32_e32 v2, v4, v0
	v_mul_f32_e32 v2, v2, v8
	v_mul_f32_e32 v0, v5, v0
	v_mul_f32_e32 v0, v0, v9
	v_cvt_pk_bf16_f32 v11, v2, v0

; __device__ __forceinline__ void phase_post(const Params& p, unsigned char* sm, const int TIDX, const int BIDX) {
;     ...
;     for (int job = BIDX; job < 1088; job += gridDim.x) {
;         const int c = job >> 2, h = job & 3;
;         const int t0 = c < 256 ? c * 64 : TP + (c - 256) * 32, nvalid = c < 256 ? 64 : 32;
;         const bool ok = r < nvalid;
;         __syncthreads();
;         {
;             const float* gg = (const float*)(p.ws + WS_GG) + (size_t)(t0 + r) * 512 + h * 128 + cseg * 16;
; #pragma unroll
;             for (int i = 0; i < 4; ++i) { float z = 0.f; asm volatile("" : "+v"(z)); f32x4 v = (f32x4){z, z, z, z}; if (ok) v = *(const f32x4*)(gg + i * 4); *(f32x4*)(Gs + r * 132 + cseg * 16 + i * 4) = v; }
;         }
;         __syncthreads();
;         { const int seg = tid >> 7, d = tid & 127; float s = 0.f;
; #pragma unroll
;           for (int i = 0; i < 16; ++i) s += Gs[(seg * 16 + i) * 132 + d];
;           SEG[seg * 128 + d] = s;
;           __syncthreads();
;           float run = 0.f;
;           for (int s2 = 0; s2 < seg; ++s2) run += SEG[s2 * 128 + d];
; #pragma unroll
;           for (int i = 0; i < 16; ++i) { run += Gs[(seg * 16 + i) * 132 + d]; Gs[(seg * 16 + i) * 132 + d] = run; }
;         }
;     ...
;         { const int d = tid >> 2, seg = tid & 3; bf16_t* KLT = (bf16_t*)(p.ws + WS_KLT) + (size_t)job * 8192 + d * 64 + seg * 16;
;           *(u32x4*)KLT = *(const u32x4*)(TTb + d * 72 + seg * 16); *(u32x4*)(KLT + 8) = *(const u32x4*)(TTb + d * 72 + seg * 16 + 8); }
;         { const int e = tid >> 1, seg = tid & 1; bf16_t* VT = (bf16_t*)(p.ws + WS_VTG) + (size_t)job * 16384 + e * 64 + seg * 32;
; #pragma unroll
;           for (int i = 0; i < 4; ++i) *(u32x4*)(VT + i * 8) = *(const u32x4*)(VV + e * 72 + seg * 32 + i * 8); }
.Lpost_tail:
	s_waitcnt lgkmcnt(0)
	s_barrier
	ds_read_b128 v[2:5], v27 offset:35840
	ds_read_b128 v[18:21], v27 offset:35856
	s_lshl_b64 s[6:7], s[20:21], 13
	v_lshl_add_u64 v[6:7], s[6:7], 1, v[12:13]
	s_waitcnt lgkmcnt(1)
	global_store_dwordx4 v[6:7], v[2:5], off
	s_waitcnt lgkmcnt(0)
	global_store_dwordx4 v[6:7], v[18:21], off offset:16
	ds_read_b128 v[2:5], v28 offset:54272
	ds_read_b128 v[18:21], v28 offset:54288
	ds_read_b128 v[40:43], v28 offset:54304
	ds_read_b128 v[44:47], v28 offset:54320
	s_lshl_b64 s[6:7], s[20:21], 15
	s_add_i32 s20, s20, s0
	v_lshl_add_u64 v[6:7], v[14:15], 0, s[6:7]
	s_cmpk_gt_i32 s20, 0x43f
	s_waitcnt lgkmcnt(3)
	global_store_dwordx4 v[6:7], v[2:5], off
	s_waitcnt lgkmcnt(2)
	global_store_dwordx4 v[6:7], v[18:21], off offset:16
	s_waitcnt lgkmcnt(1)
	global_store_dwordx4 v[6:7], v[40:43], off offset:32
	s_waitcnt lgkmcnt(0)
	global_store_dwordx4 v[6:7], v[44:47], off offset:48
	s_cbranch_scc1 .LBB0_522
.LBB0_468:
	s_ashr_i32 s6, s20, 2
	s_lshl_b32 s8, s6, 5
	s_and_b32 s3, s20, 3
	s_lshl_b32 s7, s6, 6
	s_addk_i32 s8, 0x2000
	s_cmpk_lt_i32 s6, 0x100
	s_cselect_b32 s8, s7, s8
	v_add_u32_e32 v18, s8, v36
	v_ashrrev_i32_e32 v19, 31, v18
	v_lshlrev_b64 v[6:7], 11, v[18:19]
	v_readlane_b32 s8, v254, 16
	s_cselect_b32 s6, 64, 32
	v_lshl_add_u64 v[2:3], s[10:11], 0, v[6:7]
	v_readlane_b32 s9, v254, 17
	s_lshl_b32 s8, s3, 9
	v_writelane_b32 v254, s8, 16
	v_cmp_gt_i32_e64 s[6:7], s6, v36
	s_waitcnt lgkmcnt(0)
	v_lshl_add_u64 v[2:3], v[2:3], 0, s[8:9]
	v_lshl_add_u64 v[20:21], v[2:3], 0, v[0:1]
	v_mov_b32_e32 v2, v1
	s_barrier
	v_writelane_b32 v254, s9, 17
	s_nop 0
	v_mov_b32_e32 v3, v2
	v_mov_b32_e32 v4, v2
	v_mov_b32_e32 v5, v2
	v_mov_b32_e32 v204, v1
	v_mov_b32_e32 v205, v1
	v_mov_b32_e32 v206, v1
	v_mov_b32_e32 v207, v1
	v_mov_b32_e32 v208, v1
	v_mov_b32_e32 v209, v1
	v_mov_b32_e32 v210, v1
	v_mov_b32_e32 v211, v1
	v_mov_b32_e32 v212, v1
	v_mov_b32_e32 v213, v1
	v_mov_b32_e32 v214, v1
	v_mov_b32_e32 v215, v1
	s_and_saveexec_b64 s[8:9], s[6:7]
	s_cbranch_execz .Lpost_gg_skip
	global_load_dwordx4 v[2:5], v[20:21], off
	global_load_dwordx4 v[204:207], v[20:21], off offset:16
	global_load_dwordx4 v[208:211], v[20:21], off offset:32
	global_load_dwordx4 v[212:215], v[20:21], off offset:48
.Lpost_gg_skip:
	s_or_b64 exec, exec, s[8:9]
	s_waitcnt vmcnt(0)
	ds_write_b128 v25, v[2:5]
	ds_write_b128 v25, v[204:207] offset:16
	ds_write_b128 v25, v[208:211] offset:32
	ds_write_b128 v25, v[212:215] offset:48
	s_waitcnt lgkmcnt(0)
	s_barrier
	ds_read2_b32 v[2:3], v32 offset1:132
	v_add_u32_e32 v33, 0x400, v32
	v_add_u32_e32 v34, 0x800, v32
	v_add_u32_e32 v21, 0xc00, v32
	v_add_u32_e32 v20, 0x1000, v32
	s_waitcnt lgkmcnt(0)
	v_add_f32_e32 v2, 0, v2
	v_add_f32_e32 v4, v2, v3
	ds_read2_b32 v[2:3], v33 offset0:8 offset1:140
	v_add_u32_e32 v17, 0x1400, v32
	v_add_u32_e32 v5, 0x1800, v32
	v_mov_b32_e32 v35, 0
	s_waitcnt lgkmcnt(0)
	v_add_f32_e32 v2, v4, v2
	v_add_f32_e32 v4, v2, v3
	ds_read2_b32 v[2:3], v34 offset0:16 offset1:148
	s_waitcnt lgkmcnt(0)
	v_add_f32_e32 v2, v4, v2
	v_add_f32_e32 v4, v2, v3
	ds_read2_b32 v[2:3], v21 offset0:24 offset1:156
	s_waitcnt lgkmcnt(0)
	v_add_f32_e32 v2, v4, v2
	v_add_f32_e32 v4, v2, v3
	ds_read2_b32 v[2:3], v20 offset0:32 offset1:164
	s_waitcnt lgkmcnt(0)
	v_add_f32_e32 v2, v4, v2
	v_add_f32_e32 v4, v2, v3
	ds_read2_b32 v[2:3], v17 offset0:40 offset1:172
	s_waitcnt lgkmcnt(0)
	v_add_f32_e32 v2, v4, v2
	v_add_f32_e32 v4, v2, v3
	ds_read2_b32 v[2:3], v5 offset0:48 offset1:180
	s_waitcnt lgkmcnt(0)
	v_add_f32_e32 v2, v4, v2
	v_add_u32_e32 v4, 0x1c00, v32
	v_add_f32_e32 v37, v2, v3
	ds_read2_b32 v[2:3], v4 offset0:56 offset1:188
	s_waitcnt lgkmcnt(0)
	v_add_f32_e32 v2, v37, v2
	v_add_f32_e32 v2, v2, v3
	ds_write_b32 v24, v2 offset:33792
	s_waitcnt lgkmcnt(0)
	s_barrier
	s_and_saveexec_b64 s[22:23], vcc
	s_cbranch_execz .LBB0_480
	v_mov_b32_e32 v35, 0
	s_mov_b64 s[24:25], 0
	v_mov_b32_e32 v2, v31
	v_mov_b32_e32 v3, v23

; __device__ __forceinline__ unsigned pk2(float lo, float hi) { unsigned r; asm("v_cvt_pk_bf16_f32 %0, %1, %2" : "=v"(r) : "v"(lo), "v"(hi)); return r; }
; __device__ __forceinline__ void phase_post(const Params& p, unsigned char* sm, const int TIDX, const int BIDX) {
;     ...
;             float qe[16], ke[16];
; #pragma unroll
;             for (int i = 0; i < 16; ++i) {
;                 const float b = Gs[r * 132 + cseg * 16 + i], bl = Gs[63 * 132 + cseg * 16 + i];
;                 qe[i] = q[i] * __expf(b); ke[i] = k[i] * __expf(-b);
;                 TTb[(cseg * 16 + i) * 72 + r] = (bf16_t)(pk2(k[i] * __expf(bl - b), 0.f) & 0xffffu);
;                 if (r == 63) ((float*)(p.ws + WS_EBL))[job * 128 + cseg * 16 + i] = __expf(bl);
;             }
;             bf16_t* QE = (bf16_t*)(p.ws + WS_QE) + (size_t)job * 8192 + r * 128 + cseg * 16;
;             bf16_t* KE = (bf16_t*)(p.ws + WS_KE) + (size_t)job * 8192 + r * 128 + cseg * 16;
;             u32x4 w0, w1;
;             w0.x = pk2(qe[0], qe[1]); w0.y = pk2(qe[2], qe[3]); w0.z = pk2(qe[4], qe[5]); w0.w = pk2(qe[6], qe[7]);
;             w1.x = pk2(qe[8], qe[9]); w1.y = pk2(qe[10], qe[11]); w1.z = pk2(qe[12], qe[13]); w1.w = pk2(qe[14], qe[15]);
;             *(u32x4*)QE = w0; *(u32x4*)(QE + 8) = w1;
;             w0.x = pk2(ke[0], ke[1]); w0.y = pk2(ke[2], ke[3]); w0.z = pk2(ke[4], ke[5]); w0.w = pk2(ke[6], ke[7]);
;             w1.x = pk2(ke[8], ke[9]); w1.y = pk2(ke[10], ke[11]); w1.z = pk2(ke[12], ke[13]); w1.w = pk2(ke[14], ke[15]);
;             *(u32x4*)KE = w0; *(u32x4*)(KE + 8) = w1;
;         }
;         {
;             const bf16_t* gv = (const bf16_t*)(p.ws + WS_GV) + (size_t)(t0 + r) * 1024 + h * 256 + cseg * 32;
; #pragma unroll
;             for (int i = 0; i < 4; ++i) {
;                 const u32x4 a = ok ? *(const u32x4*)(gv + i * 8) : (u32x4){0u, 0u, 0u, 0u};
;                 const int e = cseg * 32 + i * 8;
;                 VV[(e + 0) * 72 + r] = (bf16_t)(a.x & 0xffffu); VV[(e + 1) * 72 + r] = (bf16_t)(a.x >> 16);
;                 VV[(e + 2) * 72 + r] = (bf16_t)(a.y & 0xffffu); VV[(e + 3) * 72 + r] = (bf16_t)(a.y >> 16);
;                 VV[(e + 4) * 72 + r] = (bf16_t)(a.z & 0xffffu); VV[(e + 5) * 72 + r] = (bf16_t)(a.z >> 16);
;                 VV[(e + 6) * 72 + r] = (bf16_t)(a.w & 0xffffu); VV[(e + 7) * 72 + r] = (bf16_t)(a.w >> 16);
;             }
;         }
.LBB0_514:
	s_or_b64 exec, exec, s[8:9]
	v_mul_f32_e32 v2, 0x3fb8aa3b, v77
	v_exp_f32_e32 v2, v2
	s_ashr_i32 s21, s20, 31
	s_lshl_b64 s[8:9], s[20:21], 14
	v_mul_f32_e32 v52, v52, v2
	v_mul_f32_e32 v2, 0xbfb8aa3b, v77
	v_exp_f32_e32 v2, v2
	s_nop 0
	v_mul_f32_e32 v65, v65, v2
	v_mul_f32_e32 v2, 0x3fb8aa3b, v76
	v_exp_f32_e32 v2, v2
	s_nop 0
	v_mul_f32_e32 v49, v49, v2
	v_mul_f32_e32 v2, 0xbfb8aa3b, v76
	v_exp_f32_e32 v2, v2
	s_nop 0
	v_mul_f32_e32 v63, v63, v2
	v_mul_f32_e32 v2, 0x3fb8aa3b, v75
	v_exp_f32_e32 v2, v2
	s_nop 0
	v_mul_f32_e32 v47, v47, v2
	v_mul_f32_e32 v2, 0xbfb8aa3b, v75
	v_exp_f32_e32 v2, v2
	s_nop 0
	v_mul_f32_e32 v62, v62, v2
	v_mul_f32_e32 v2, 0x3fb8aa3b, v74
	v_exp_f32_e32 v2, v2
	s_nop 0
	v_mul_f32_e32 v45, v45, v2
	v_mul_f32_e32 v2, 0xbfb8aa3b, v74
	v_exp_f32_e32 v2, v2
	s_nop 0
	v_mul_f32_e32 v60, v60, v2
	v_mul_f32_e32 v2, 0x3fb8aa3b, v73
	v_exp_f32_e32 v2, v2
	s_nop 0
	v_mul_f32_e32 v43, v43, v2
	v_mul_f32_e32 v2, 0xbfb8aa3b, v73
	v_exp_f32_e32 v2, v2
	s_nop 0
	v_mul_f32_e32 v59, v59, v2
	v_mul_f32_e32 v2, 0x3fb8aa3b, v72
	v_exp_f32_e32 v2, v2
	s_nop 0
	v_mul_f32_e32 v69, v41, v2
	v_mul_f32_e32 v2, 0xbfb8aa3b, v72
	v_exp_f32_e32 v2, v2
	s_nop 0
	v_mul_f32_e32 v57, v57, v2
	v_mul_f32_e32 v2, 0x3fb8aa3b, v71
	v_exp_f32_e32 v2, v2
	s_nop 0
	v_mul_f32_e32 v37, v37, v2
	v_mul_f32_e32 v2, 0xbfb8aa3b, v71
	v_exp_f32_e32 v2, v2
	s_nop 0
	v_mul_f32_e32 v56, v56, v2
	v_mul_f32_e32 v2, 0x3fb8aa3b, v70
	v_exp_f32_e32 v2, v2
	s_nop 0
	v_mul_f32_e32 v71, v34, v2
	v_mul_f32_e32 v2, 0xbfb8aa3b, v70
	v_exp_f32_e32 v2, v2
	s_nop 0
	v_mul_f32_e32 v54, v54, v2
	v_mul_f32_e32 v2, 0x3fb8aa3b, v68
	v_exp_f32_e32 v2, v2
	s_nop 0
	v_mul_f32_e32 v33, v33, v2
	v_mul_f32_e32 v2, 0xbfb8aa3b, v68
	v_exp_f32_e32 v2, v2
	s_nop 0
	v_mul_f32_e32 v53, v53, v2
	v_mul_f32_e32 v2, 0x3fb8aa3b, v67
	v_exp_f32_e32 v2, v2
	s_nop 0
	v_mul_f32_e32 v21, v21, v2
	v_mul_f32_e32 v2, 0xbfb8aa3b, v67
	v_exp_f32_e32 v2, v2
	s_nop 0
	v_mul_f32_e32 v50, v50, v2
	v_mul_f32_e32 v2, 0x3fb8aa3b, v66
	v_exp_f32_e32 v2, v2
	s_nop 0
	v_mul_f32_e32 v20, v20, v2
	v_mul_f32_e32 v2, 0xbfb8aa3b, v66
	v_exp_f32_e32 v2, v2
	s_nop 0
	v_mul_f32_e32 v48, v48, v2
	v_mul_f32_e32 v2, 0x3fb8aa3b, v64
	v_exp_f32_e32 v2, v2
	s_nop 0
	v_mul_f32_e32 v19, v19, v2
	v_mul_f32_e32 v2, 0xbfb8aa3b, v64
	v_exp_f32_e32 v2, v2
	s_nop 0
	v_mul_f32_e32 v46, v46, v2
	v_mul_f32_e32 v2, 0x3fb8aa3b, v61
	v_exp_f32_e32 v2, v2
	s_nop 0
	v_mul_f32_e32 v3, v18, v2
	v_mul_f32_e32 v2, 0xbfb8aa3b, v61
	v_exp_f32_e32 v2, v2
	v_cvt_pk_bf16_f32 v18, v71, v37
	s_nop 0
	v_mul_f32_e32 v44, v44, v2
	v_mul_f32_e32 v2, 0x3fb8aa3b, v58
	v_exp_f32_e32 v2, v2
	s_nop 0
	v_mul_f32_e32 v17, v17, v2
	v_mul_f32_e32 v2, 0xbfb8aa3b, v58
	v_exp_f32_e32 v2, v2
	v_cvt_pk_bf16_f32 v3, v17, v3
	v_mov_b32_e32 v17, v1
	v_mul_f32_e32 v42, v42, v2
	v_mul_f32_e32 v2, 0x3fb8aa3b, v55
	v_exp_f32_e32 v2, v2
	s_nop 0
	v_mul_f32_e32 v2, v5, v2
	v_mul_f32_e32 v5, 0xbfb8aa3b, v55
	v_exp_f32_e32 v5, v5
	s_nop 0
	v_mul_f32_e32 v55, v40, v5
	v_mul_f32_e32 v5, 0x3fb8aa3b, v51
	v_exp_f32_e32 v5, v5
	v_lshl_add_u64 v[40:41], v[10:11], 0, s[8:9]
	v_mul_f32_e32 v4, v4, v5
	v_mul_f32_e32 v5, 0xbfb8aa3b, v51
	v_exp_f32_e32 v5, v5
	v_cvt_pk_bf16_f32 v2, v4, v2
	v_cvt_pk_bf16_f32 v4, v19, v20
	v_cvt_pk_bf16_f32 v19, v69, v43
	v_cvt_pk_bf16_f32 v20, v45, v47
	s_nop 0
	v_mul_f32_e32 v51, v35, v5
	v_lshl_add_u64 v[34:35], v[8:9], 0, s[8:9]
	v_cvt_pk_bf16_f32 v5, v21, v33
	v_cvt_pk_bf16_f32 v21, v49, v52
	global_store_dwordx4 v[34:35], v[2:5], off
	global_store_dwordx4 v[34:35], v[18:21], off offset:16
	v_readlane_b32 s8, v254, 16
	v_cvt_pk_bf16_f32 v2, v51, v55
	v_cvt_pk_bf16_f32 v3, v42, v44
	v_cvt_pk_bf16_f32 v4, v46, v48
	v_cvt_pk_bf16_f32 v5, v50, v53
	s_nop 0
	v_cvt_pk_bf16_f32 v18, v54, v56
	v_cvt_pk_bf16_f32 v19, v57, v59
	v_cvt_pk_bf16_f32 v20, v60, v62
	v_cvt_pk_bf16_f32 v21, v63, v65
	global_store_dwordx4 v[40:41], v[2:5], off
	global_store_dwordx4 v[40:41], v[18:21], off offset:16
	v_readlane_b32 s9, v254, 17
	v_lshl_add_u64 v[2:3], s[18:19], 0, v[6:7]
	v_mov_b32_e32 v4, 0
	v_lshl_add_u64 v[2:3], v[2:3], 0, s[8:9]
	v_lshl_add_u64 v[18:19], v[2:3], 0, v[16:17]
	v_mov_b32_e32 v204, 0
	v_mov_b32_e32 v205, 0
	v_mov_b32_e32 v206, 0
	v_mov_b32_e32 v207, 0
	v_mov_b32_e32 v208, 0
	v_mov_b32_e32 v209, 0
	v_mov_b32_e32 v210, 0
	v_mov_b32_e32 v211, 0
	v_mov_b32_e32 v212, 0
	v_mov_b32_e32 v213, 0
	v_mov_b32_e32 v214, 0
	v_mov_b32_e32 v215, 0
	v_mov_b32_e32 v216, 0
	v_mov_b32_e32 v217, 0
	v_mov_b32_e32 v218, 0
	v_mov_b32_e32 v219, 0
	s_and_saveexec_b64 s[8:9], s[6:7]
	s_cbranch_execz .Lpost_gv_skip
	global_load_dwordx4 v[204:207], v[18:19], off
	global_load_dwordx4 v[208:211], v[18:19], off offset:16
	global_load_dwordx4 v[212:215], v[18:19], off offset:32
	global_load_dwordx4 v[216:219], v[18:19], off offset:48
.Lpost_gv_skip:
	s_or_b64 exec, exec, s[8:9]
	s_waitcnt vmcnt(0)
	ds_write_b16 v29, v204 offset:54272
	ds_write_b16_d16_hi v30, v204 offset:54416
	ds_write_b16 v30, v205 offset:54560
	ds_write_b16_d16_hi v30, v205 offset:54704
	ds_write_b16 v30, v206 offset:54848
	ds_write_b16_d16_hi v30, v206 offset:54992
	ds_write_b16 v30, v207 offset:55136
	ds_write_b16_d16_hi v30, v207 offset:55280
	ds_write_b16 v29, v208 offset:55424
	ds_write_b16_d16_hi v30, v208 offset:55568
	ds_write_b16 v30, v209 offset:55712
	ds_write_b16_d16_hi v30, v209 offset:55856
	ds_write_b16 v30, v210 offset:56000
	ds_write_b16_d16_hi v30, v210 offset:56144
	ds_write_b16 v30, v211 offset:56288
	ds_write_b16_d16_hi v30, v211 offset:56432
	ds_write_b16 v29, v212 offset:56576
	ds_write_b16_d16_hi v30, v212 offset:56720
	ds_write_b16 v30, v213 offset:56864
	ds_write_b16_d16_hi v30, v213 offset:57008
	ds_write_b16 v30, v214 offset:57152
	ds_write_b16_d16_hi v30, v214 offset:57296
	ds_write_b16 v30, v215 offset:57440
	ds_write_b16_d16_hi v30, v215 offset:57584
	ds_write_b16 v29, v216 offset:57728
	ds_write_b16_d16_hi v30, v216 offset:57872
	ds_write_b16 v30, v217 offset:58016
	ds_write_b16_d16_hi v30, v217 offset:58160
	ds_write_b16 v30, v218 offset:58304
	ds_write_b16_d16_hi v30, v218 offset:58448
	ds_write_b16 v30, v219 offset:58592
	ds_write_b16_d16_hi v30, v219 offset:58736
	s_branch .Lpost_tail
